# cv_finish: 32 per-element norm-gain loads (each with vmcnt(0)) batched into one group; PV-MFMA hoist over row-max tree in attention main loop; SGU load batching
# speedup vs baseline: 1.0148x; 1.0083x over previous
.LBB0_28:
	s_cmp_eq_u32 s26, 1
	s_cselect_b64 s[6:7], -1, 0
	s_cmpk_lt_i32 s34, 0x200
	s_cselect_b64 s[50:51], -1, 0
	s_and_b64 vcc, s[50:51], s[6:7]
	s_cmp_lg_u32 s26, 0
	v_cndmask_b32_e32 v78, 1.0, v13, vcc
	s_cselect_b64 s[50:51], -1, 0
	s_cmp_eq_u32 s26, 0
	s_cbranch_scc1 .LBB0_30
	v_or_b32_e32 v80, s40, v2
	v_ashrrev_i32_e32 v81, 31, v80
	v_lshl_add_u64 v[80:81], v[80:81], 2, s[38:39]
	global_load_dword v96, v[80:81], off
	global_load_dword v97, v[80:81], off offset:8
	global_load_dword v98, v[80:81], off offset:16
	global_load_dword v99, v[80:81], off offset:24
	global_load_dword v100, v[80:81], off offset:32
	global_load_dword v101, v[80:81], off offset:40
	global_load_dword v102, v[80:81], off offset:48
	global_load_dword v103, v[80:81], off offset:56
	global_load_dword v104, v[80:81], off offset:64
	global_load_dword v105, v[80:81], off offset:72
	global_load_dword v106, v[80:81], off offset:80
	global_load_dword v107, v[80:81], off offset:88
	global_load_dword v108, v[80:81], off offset:96
	global_load_dword v109, v[80:81], off offset:104
	global_load_dword v110, v[80:81], off offset:112
	global_load_dword v111, v[80:81], off offset:120
	global_load_dword v112, v[80:81], off offset:128
	global_load_dword v113, v[80:81], off offset:136
	global_load_dword v114, v[80:81], off offset:144
	global_load_dword v115, v[80:81], off offset:152
	global_load_dword v116, v[80:81], off offset:160
	global_load_dword v117, v[80:81], off offset:168
	global_load_dword v118, v[80:81], off offset:176
	global_load_dword v119, v[80:81], off offset:184
	global_load_dword v120, v[80:81], off offset:192
	global_load_dword v121, v[80:81], off offset:200
	global_load_dword v122, v[80:81], off offset:208
	global_load_dword v123, v[80:81], off offset:216
	global_load_dword v124, v[80:81], off offset:224
	global_load_dword v125, v[80:81], off offset:232
	global_load_dword v126, v[80:81], off offset:240
	global_load_dword v127, v[80:81], off offset:248
	s_waitcnt vmcnt(31)
	v_mov_b32_e32 v79, v96
	v_mul_f32_e32 v79, v78, v79
	v_mul_f32_e32 v77, v77, v79
.LBB0_30:
	v_cndmask_b32_e64 v79, 0, 1, s[50:51]
	v_cmp_ne_u32_e64 s[6:7], 1, v79
	s_andn2_b64 vcc, exec, s[50:51]
	s_waitcnt vmcnt(31)
	ds_write_b32 v14, v77
	s_cbranch_vccnz .LBB0_32
	s_ashr_i32 s41, s40, 31
	v_lshl_add_u64 v[80:81], s[40:41], 0, v[2:3]
	v_lshl_add_u64 v[80:81], v[80:81], 2, s[38:39]
	s_waitcnt vmcnt(30)
	v_mov_b32_e32 v77, v97
	v_mul_f32_e32 v77, v78, v77
	v_mul_f32_e32 v76, v76, v77
.LBB0_32:
	s_and_b64 vcc, exec, s[6:7]
	s_waitcnt vmcnt(30)
	ds_write_b32 v14, v76 offset:264
	s_cbranch_vccnz .LBB0_34
	s_ashr_i32 s41, s40, 31
	v_lshl_add_u64 v[76:77], s[40:41], 0, v[2:3]
	v_lshl_add_u64 v[76:77], v[76:77], 2, s[38:39]
	s_waitcnt vmcnt(29)
	v_mov_b32_e32 v76, v98
	v_mul_f32_e32 v76, v78, v76
	v_mul_f32_e32 v75, v75, v76
.LBB0_34:
	s_and_b64 vcc, exec, s[6:7]
	s_waitcnt vmcnt(29)
	ds_write_b32 v14, v75 offset:528
	s_cbranch_vccnz .LBB0_36
	s_ashr_i32 s41, s40, 31
	v_lshl_add_u64 v[76:77], s[40:41], 0, v[2:3]
	v_lshl_add_u64 v[76:77], v[76:77], 2, s[38:39]
	s_waitcnt vmcnt(28)
	v_mov_b32_e32 v75, v99
	v_mul_f32_e32 v75, v78, v75
	v_mul_f32_e32 v74, v74, v75
.LBB0_36:
	s_and_b64 vcc, exec, s[6:7]
	s_waitcnt vmcnt(28)
	ds_write_b32 v14, v74 offset:792
	s_cbranch_vccnz .LBB0_38
	s_ashr_i32 s41, s40, 31
	v_lshl_add_u64 v[74:75], s[40:41], 0, v[2:3]
	v_lshl_add_u64 v[74:75], v[74:75], 2, s[38:39]
	s_waitcnt vmcnt(27)
	v_mov_b32_e32 v74, v100
	v_mul_f32_e32 v74, v78, v74
	v_mul_f32_e32 v73, v73, v74
.LBB0_38:
	s_and_b64 vcc, exec, s[6:7]
	s_waitcnt vmcnt(27)
	ds_write_b32 v14, v73 offset:1056
	s_cbranch_vccnz .LBB0_40
	s_ashr_i32 s41, s40, 31
	v_lshl_add_u64 v[74:75], s[40:41], 0, v[2:3]
	v_lshl_add_u64 v[74:75], v[74:75], 2, s[38:39]
	s_waitcnt vmcnt(26)
	v_mov_b32_e32 v73, v101
	v_mul_f32_e32 v73, v78, v73
	v_mul_f32_e32 v63, v63, v73
.LBB0_40:
	s_and_b64 vcc, exec, s[6:7]
	s_waitcnt vmcnt(26)
	ds_write_b32 v14, v63 offset:1320
	s_cbranch_vccnz .LBB0_42
	s_ashr_i32 s41, s40, 31
	v_lshl_add_u64 v[74:75], s[40:41], 0, v[2:3]
	v_lshl_add_u64 v[74:75], v[74:75], 2, s[38:39]
	s_waitcnt vmcnt(25)
	v_mov_b32_e32 v63, v102
	v_mul_f32_e32 v63, v78, v63
	v_mul_f32_e32 v59, v59, v63
.LBB0_42:
	s_and_b64 vcc, exec, s[6:7]
	s_waitcnt vmcnt(25)
	ds_write_b32 v14, v59 offset:1584
	s_cbranch_vccnz .LBB0_44
	s_ashr_i32 s41, s40, 31
	v_lshl_add_u64 v[74:75], s[40:41], 0, v[2:3]
	v_lshl_add_u64 v[74:75], v[74:75], 2, s[38:39]
	s_waitcnt vmcnt(24)
	v_mov_b32_e32 v59, v103
	v_mul_f32_e32 v59, v78, v59
	v_mul_f32_e32 v57, v57, v59
.LBB0_44:
	s_and_b64 vcc, exec, s[6:7]
	s_waitcnt vmcnt(24)
	ds_write_b32 v14, v57 offset:1848
	s_cbranch_vccnz .LBB0_46
	s_ashr_i32 s41, s40, 31
	v_lshl_add_u64 v[74:75], s[40:41], 0, v[2:3]
	v_lshl_add_u64 v[74:75], v[74:75], 2, s[38:39]
	s_waitcnt vmcnt(23)
	v_mov_b32_e32 v57, v104
	v_mul_f32_e32 v57, v78, v57
	v_mul_f32_e32 v72, v72, v57
.LBB0_46:
	s_and_b64 vcc, exec, s[6:7]
	s_waitcnt vmcnt(23)
	ds_write_b32 v14, v72 offset:2112
	s_cbranch_vccnz .LBB0_48
	s_ashr_i32 s41, s40, 31
	v_lshl_add_u64 v[72:73], s[40:41], 0, v[2:3]
	v_lshl_add_u64 v[72:73], v[72:73], 2, s[38:39]
	s_waitcnt vmcnt(22)
	v_mov_b32_e32 v57, v105
	v_mul_f32_e32 v57, v78, v57
	v_mul_f32_e32 v62, v62, v57
.LBB0_48:
	s_and_b64 vcc, exec, s[6:7]
	s_waitcnt vmcnt(22)
	ds_write_b32 v14, v62 offset:2376
	s_cbranch_vccnz .LBB0_50
	s_ashr_i32 s41, s40, 31
	v_lshl_add_u64 v[62:63], s[40:41], 0, v[2:3]
	v_lshl_add_u64 v[62:63], v[62:63], 2, s[38:39]
	s_waitcnt vmcnt(21)
	v_mov_b32_e32 v57, v106
	v_mul_f32_e32 v57, v78, v57
	v_mul_f32_e32 v58, v58, v57
.LBB0_50:
	s_and_b64 vcc, exec, s[6:7]
	s_waitcnt vmcnt(21)
	ds_write_b32 v14, v58 offset:2640
	s_cbranch_vccnz .LBB0_52
	s_ashr_i32 s41, s40, 31
	v_lshl_add_u64 v[58:59], s[40:41], 0, v[2:3]
	v_lshl_add_u64 v[58:59], v[58:59], 2, s[38:39]
	s_waitcnt vmcnt(20)
	v_mov_b32_e32 v57, v107
	v_mul_f32_e32 v57, v78, v57
	v_mul_f32_e32 v56, v56, v57
.LBB0_52:
	s_and_b64 vcc, exec, s[6:7]
	s_waitcnt vmcnt(20)
	ds_write_b32 v14, v56 offset:2904
	s_cbranch_vccnz .LBB0_54
	s_ashr_i32 s41, s40, 31
	v_lshl_add_u64 v[56:57], s[40:41], 0, v[2:3]
	v_lshl_add_u64 v[56:57], v[56:57], 2, s[38:39]
	s_waitcnt vmcnt(19)
	v_mov_b32_e32 v56, v108
	v_mul_f32_e32 v56, v78, v56
	v_mul_f32_e32 v49, v49, v56
.LBB0_54:
	s_and_b64 vcc, exec, s[6:7]
	s_waitcnt vmcnt(19)
	ds_write_b32 v14, v49 offset:3168
	s_cbranch_vccnz .LBB0_56
	s_ashr_i32 s41, s40, 31
	v_lshl_add_u64 v[56:57], s[40:41], 0, v[2:3]
	v_lshl_add_u64 v[56:57], v[56:57], 2, s[38:39]
	s_waitcnt vmcnt(18)
	v_mov_b32_e32 v49, v109
	v_mul_f32_e32 v49, v78, v49
	v_mul_f32_e32 v39, v39, v49
.LBB0_56:
	s_and_b64 vcc, exec, s[6:7]
	s_waitcnt vmcnt(18)
	ds_write_b32 v14, v39 offset:3432
	s_cbranch_vccnz .LBB0_58
	s_ashr_i32 s41, s40, 31
	v_lshl_add_u64 v[56:57], s[40:41], 0, v[2:3]
	v_lshl_add_u64 v[56:57], v[56:57], 2, s[38:39]
	s_waitcnt vmcnt(17)
	v_mov_b32_e32 v39, v110
	v_mul_f32_e32 v39, v78, v39
	v_mul_f32_e32 v37, v37, v39
.LBB0_58:
	s_and_b64 vcc, exec, s[6:7]
	s_waitcnt vmcnt(17)
	ds_write_b32 v14, v37 offset:3696
	s_cbranch_vccnz .LBB0_60
	s_ashr_i32 s41, s40, 31
	v_lshl_add_u64 v[56:57], s[40:41], 0, v[2:3]
	v_lshl_add_u64 v[56:57], v[56:57], 2, s[38:39]
	s_waitcnt vmcnt(16)
	v_mov_b32_e32 v37, v111
	v_mul_f32_e32 v37, v78, v37
	v_mul_f32_e32 v35, v35, v37
.LBB0_60:
	s_and_b64 vcc, exec, s[6:7]
	s_waitcnt vmcnt(16)
	ds_write_b32 v14, v35 offset:3960
	s_cbranch_vccnz .LBB0_62
	s_ashr_i32 s41, s40, 31
	v_lshl_add_u64 v[56:57], s[40:41], 0, v[2:3]
	v_lshl_add_u64 v[56:57], v[56:57], 2, s[38:39]
	s_waitcnt vmcnt(15)
	v_mov_b32_e32 v35, v112
	v_mul_f32_e32 v35, v78, v35
	v_mul_f32_e32 v48, v48, v35
.LBB0_62:
	s_and_b64 vcc, exec, s[6:7]
	s_waitcnt vmcnt(15)
	ds_write_b32 v14, v48 offset:4224
	s_cbranch_vccnz .LBB0_64
	s_ashr_i32 s41, s40, 31
	v_lshl_add_u64 v[48:49], s[40:41], 0, v[2:3]
	v_lshl_add_u64 v[48:49], v[48:49], 2, s[38:39]
	s_waitcnt vmcnt(14)
	v_mov_b32_e32 v35, v113
	v_mul_f32_e32 v35, v78, v35
	v_mul_f32_e32 v38, v38, v35
.LBB0_64:
	s_and_b64 vcc, exec, s[6:7]
	s_waitcnt vmcnt(14)
	ds_write_b32 v14, v38 offset:4488
	s_cbranch_vccnz .LBB0_66
	s_ashr_i32 s41, s40, 31
	v_lshl_add_u64 v[38:39], s[40:41], 0, v[2:3]
	v_lshl_add_u64 v[38:39], v[38:39], 2, s[38:39]
	s_waitcnt vmcnt(13)
	v_mov_b32_e32 v35, v114
	v_mul_f32_e32 v35, v78, v35
	v_mul_f32_e32 v36, v36, v35
.LBB0_66:
	s_and_b64 vcc, exec, s[6:7]
	s_waitcnt vmcnt(13)
	ds_write_b32 v14, v36 offset:4752
	s_cbranch_vccnz .LBB0_68
	s_ashr_i32 s41, s40, 31
	v_lshl_add_u64 v[36:37], s[40:41], 0, v[2:3]
	v_lshl_add_u64 v[36:37], v[36:37], 2, s[38:39]
	s_waitcnt vmcnt(12)
	v_mov_b32_e32 v35, v115
	v_mul_f32_e32 v35, v78, v35
	v_mul_f32_e32 v34, v34, v35
.LBB0_68:
	s_and_b64 vcc, exec, s[6:7]
	s_waitcnt vmcnt(12)
	ds_write_b32 v14, v34 offset:5016
	s_cbranch_vccnz .LBB0_70
	s_ashr_i32 s41, s40, 31
	v_lshl_add_u64 v[34:35], s[40:41], 0, v[2:3]
	v_lshl_add_u64 v[34:35], v[34:35], 2, s[38:39]
	s_waitcnt vmcnt(11)
	v_mov_b32_e32 v34, v116
	v_mul_f32_e32 v34, v78, v34
	v_mul_f32_e32 v26, v26, v34
.LBB0_70:
	s_and_b64 vcc, exec, s[6:7]
	s_waitcnt vmcnt(11)
	ds_write_b32 v14, v26 offset:5280
	s_cbranch_vccnz .LBB0_72
	s_ashr_i32 s41, s40, 31
	v_lshl_add_u64 v[34:35], s[40:41], 0, v[2:3]
	v_lshl_add_u64 v[34:35], v[34:35], 2, s[38:39]
	s_waitcnt vmcnt(10)
	v_mov_b32_e32 v26, v117
	v_mul_f32_e32 v26, v78, v26
	v_mul_f32_e32 v24, v24, v26
.LBB0_72:
	s_and_b64 vcc, exec, s[6:7]
	s_waitcnt vmcnt(10)
	ds_write_b32 v14, v24 offset:5544
	s_cbranch_vccnz .LBB0_74
	s_ashr_i32 s41, s40, 31
	v_lshl_add_u64 v[34:35], s[40:41], 0, v[2:3]
	v_lshl_add_u64 v[34:35], v[34:35], 2, s[38:39]
	s_waitcnt vmcnt(9)
	v_mov_b32_e32 v24, v118
	v_mul_f32_e32 v24, v78, v24
	v_mul_f32_e32 v22, v22, v24
.LBB0_74:
	s_and_b64 vcc, exec, s[6:7]
	s_waitcnt vmcnt(9)
	ds_write_b32 v14, v22 offset:5808
	s_cbranch_vccnz .LBB0_76
	s_ashr_i32 s41, s40, 31
	v_lshl_add_u64 v[34:35], s[40:41], 0, v[2:3]
	v_lshl_add_u64 v[34:35], v[34:35], 2, s[38:39]
	s_waitcnt vmcnt(8)
	v_mov_b32_e32 v22, v119
	v_mul_f32_e32 v22, v78, v22
	v_mul_f32_e32 v20, v20, v22
.LBB0_76:
	s_and_b64 vcc, exec, s[6:7]
	s_waitcnt vmcnt(8)
	ds_write_b32 v14, v20 offset:6072
	s_cbranch_vccnz .LBB0_78
	s_ashr_i32 s41, s40, 31
	v_lshl_add_u64 v[34:35], s[40:41], 0, v[2:3]
	v_lshl_add_u64 v[34:35], v[34:35], 2, s[38:39]
	s_waitcnt vmcnt(7)
	v_mov_b32_e32 v20, v120
	v_mul_f32_e32 v20, v78, v20
	v_mul_f32_e32 v25, v25, v20
.LBB0_78:
	s_and_b64 vcc, exec, s[6:7]
	s_waitcnt vmcnt(7)
	ds_write_b32 v14, v25 offset:6336
	s_cbranch_vccnz .LBB0_80
	s_ashr_i32 s41, s40, 31
	v_lshl_add_u64 v[24:25], s[40:41], 0, v[2:3]
	v_lshl_add_u64 v[24:25], v[24:25], 2, s[38:39]
	s_waitcnt vmcnt(6)
	v_mov_b32_e32 v20, v121
	v_mul_f32_e32 v20, v78, v20
	v_mul_f32_e32 v23, v23, v20
.LBB0_80:
	s_and_b64 vcc, exec, s[6:7]
	s_waitcnt vmcnt(6)
	ds_write_b32 v14, v23 offset:6600
	s_cbranch_vccnz .LBB0_82
	s_ashr_i32 s41, s40, 31
	v_lshl_add_u64 v[22:23], s[40:41], 0, v[2:3]
	v_lshl_add_u64 v[22:23], v[22:23], 2, s[38:39]
	s_waitcnt vmcnt(5)
	v_mov_b32_e32 v20, v122
	v_mul_f32_e32 v20, v78, v20
	v_mul_f32_e32 v21, v21, v20
.LBB0_82:
	s_and_b64 vcc, exec, s[6:7]
	s_waitcnt vmcnt(5)
	ds_write_b32 v14, v21 offset:6864
	s_cbranch_vccnz .LBB0_84
	s_ashr_i32 s41, s40, 31
	v_lshl_add_u64 v[20:21], s[40:41], 0, v[2:3]
	v_lshl_add_u64 v[20:21], v[20:21], 2, s[38:39]
	s_waitcnt vmcnt(4)
	v_mov_b32_e32 v20, v123
	v_mul_f32_e32 v20, v78, v20
	v_mul_f32_e32 v19, v19, v20
.LBB0_84:
	s_and_b64 vcc, exec, s[6:7]
	s_waitcnt vmcnt(4)
	ds_write_b32 v14, v19 offset:7128
	s_cbranch_vccnz .LBB0_86
	s_ashr_i32 s41, s40, 31
	v_lshl_add_u64 v[20:21], s[40:41], 0, v[2:3]
	v_lshl_add_u64 v[20:21], v[20:21], 2, s[38:39]
	s_waitcnt vmcnt(3)
	v_mov_b32_e32 v19, v124
	v_mul_f32_e32 v19, v78, v19
	v_mul_f32_e32 v18, v18, v19
.LBB0_86:
	s_and_b64 vcc, exec, s[6:7]
	s_waitcnt vmcnt(3)
	ds_write_b32 v14, v18 offset:7392
	s_cbranch_vccnz .LBB0_88
	s_ashr_i32 s41, s40, 31
	v_lshl_add_u64 v[18:19], s[40:41], 0, v[2:3]
	v_lshl_add_u64 v[18:19], v[18:19], 2, s[38:39]
	s_waitcnt vmcnt(2)
	v_mov_b32_e32 v18, v125
	v_mul_f32_e32 v18, v78, v18
	v_mul_f32_e32 v17, v17, v18
.LBB0_88:
	s_and_b64 vcc, exec, s[6:7]
	s_waitcnt vmcnt(2)
	ds_write_b32 v14, v17 offset:7656
	s_cbranch_vccnz .LBB0_90
	s_ashr_i32 s41, s40, 31
	v_lshl_add_u64 v[18:19], s[40:41], 0, v[2:3]
	v_lshl_add_u64 v[18:19], v[18:19], 2, s[38:39]
	s_waitcnt vmcnt(1)
	v_mov_b32_e32 v17, v126
	v_mul_f32_e32 v17, v78, v17
	v_mul_f32_e32 v16, v16, v17
.LBB0_90:
	s_and_b64 vcc, exec, s[6:7]
	s_waitcnt vmcnt(1)
	ds_write_b32 v14, v16 offset:7920
	s_cbranch_vccnz .LBB0_92
	s_ashr_i32 s41, s40, 31
	v_lshl_add_u64 v[16:17], s[40:41], 0, v[2:3]
	v_lshl_add_u64 v[16:17], v[16:17], 2, s[38:39]
	s_waitcnt vmcnt(0)
	v_mov_b32_e32 v16, v127
	v_mul_f32_e32 v16, v78, v16
	v_mul_f32_e32 v15, v15, v16

.LBB0_322:
	s_cmp_eq_u32 s26, 1
	s_cselect_b64 s[8:9], -1, 0
	s_cmpk_lt_i32 s46, 0x200
	s_cselect_b64 s[60:61], -1, 0
	s_and_b64 vcc, s[60:61], s[8:9]
	s_cmp_lg_u32 s26, 0
	v_cndmask_b32_e32 v76, 1.0, v11, vcc
	s_cselect_b64 s[60:61], -1, 0
	s_cmp_eq_u32 s26, 0
	s_cbranch_scc1 .LBB0_324
	v_or_b32_e32 v78, s50, v0
	v_ashrrev_i32_e32 v79, 31, v78
	v_lshl_add_u64 v[78:79], v[78:79], 2, s[48:49]
	global_load_dword v96, v[78:79], off
	global_load_dword v97, v[78:79], off offset:8
	global_load_dword v98, v[78:79], off offset:16
	global_load_dword v99, v[78:79], off offset:24
	global_load_dword v100, v[78:79], off offset:32
	global_load_dword v101, v[78:79], off offset:40
	global_load_dword v102, v[78:79], off offset:48
	global_load_dword v103, v[78:79], off offset:56
	global_load_dword v104, v[78:79], off offset:64
	global_load_dword v105, v[78:79], off offset:72
	global_load_dword v106, v[78:79], off offset:80
	global_load_dword v107, v[78:79], off offset:88
	global_load_dword v108, v[78:79], off offset:96
	global_load_dword v109, v[78:79], off offset:104
	global_load_dword v110, v[78:79], off offset:112
	global_load_dword v111, v[78:79], off offset:120
	global_load_dword v112, v[78:79], off offset:128
	global_load_dword v113, v[78:79], off offset:136
	global_load_dword v114, v[78:79], off offset:144
	global_load_dword v115, v[78:79], off offset:152
	global_load_dword v116, v[78:79], off offset:160
	global_load_dword v117, v[78:79], off offset:168
	global_load_dword v118, v[78:79], off offset:176
	global_load_dword v119, v[78:79], off offset:184
	global_load_dword v120, v[78:79], off offset:192
	global_load_dword v121, v[78:79], off offset:200
	global_load_dword v122, v[78:79], off offset:208
	global_load_dword v123, v[78:79], off offset:216
	global_load_dword v124, v[78:79], off offset:224
	global_load_dword v125, v[78:79], off offset:232
	global_load_dword v126, v[78:79], off offset:240
	global_load_dword v127, v[78:79], off offset:248
	s_waitcnt vmcnt(31)
	v_mov_b32_e32 v77, v96
	v_mul_f32_e32 v77, v76, v77
	v_mul_f32_e32 v75, v75, v77
.LBB0_324:
	v_cndmask_b32_e64 v77, 0, 1, s[60:61]
	v_cmp_ne_u32_e64 s[8:9], 1, v77
	s_andn2_b64 vcc, exec, s[60:61]
	s_waitcnt vmcnt(0)
	ds_write_b32 v12, v75
	s_cbranch_vccnz .LBB0_326
	s_ashr_i32 s51, s50, 31
	v_lshl_add_u64 v[78:79], s[50:51], 0, v[0:1]
	v_lshl_add_u64 v[78:79], v[78:79], 2, s[48:49]
	s_waitcnt vmcnt(30)
	v_mov_b32_e32 v75, v97
	v_mul_f32_e32 v75, v76, v75
	v_mul_f32_e32 v74, v74, v75
.LBB0_326:
	s_and_b64 vcc, exec, s[8:9]
	ds_write_b32 v12, v74 offset:264
	s_cbranch_vccnz .LBB0_328
	s_ashr_i32 s51, s50, 31
	v_lshl_add_u64 v[74:75], s[50:51], 0, v[0:1]
	v_lshl_add_u64 v[74:75], v[74:75], 2, s[48:49]
	s_waitcnt vmcnt(29)
	v_mov_b32_e32 v74, v98
	v_mul_f32_e32 v74, v76, v74
	v_mul_f32_e32 v73, v73, v74
.LBB0_328:
	s_and_b64 vcc, exec, s[8:9]
	ds_write_b32 v12, v73 offset:528
	s_cbranch_vccnz .LBB0_330
	s_ashr_i32 s51, s50, 31
	v_lshl_add_u64 v[74:75], s[50:51], 0, v[0:1]
	v_lshl_add_u64 v[74:75], v[74:75], 2, s[48:49]
	s_waitcnt vmcnt(28)
	v_mov_b32_e32 v73, v99
	v_mul_f32_e32 v73, v76, v73
	v_mul_f32_e32 v72, v72, v73
.LBB0_330:
	s_and_b64 vcc, exec, s[8:9]
	ds_write_b32 v12, v72 offset:792
	s_cbranch_vccnz .LBB0_332
	s_ashr_i32 s51, s50, 31
	v_lshl_add_u64 v[72:73], s[50:51], 0, v[0:1]
	v_lshl_add_u64 v[72:73], v[72:73], 2, s[48:49]
	s_waitcnt vmcnt(27)
	v_mov_b32_e32 v72, v100
	v_mul_f32_e32 v72, v76, v72
	v_mul_f32_e32 v71, v71, v72
.LBB0_332:
	s_and_b64 vcc, exec, s[8:9]
	ds_write_b32 v12, v71 offset:1056
	s_cbranch_vccnz .LBB0_334
	s_ashr_i32 s51, s50, 31
	v_lshl_add_u64 v[72:73], s[50:51], 0, v[0:1]
	v_lshl_add_u64 v[72:73], v[72:73], 2, s[48:49]
	s_waitcnt vmcnt(26)
	v_mov_b32_e32 v71, v101
	v_mul_f32_e32 v71, v76, v71
	v_mul_f32_e32 v69, v69, v71
.LBB0_334:
	s_and_b64 vcc, exec, s[8:9]
	ds_write_b32 v12, v69 offset:1320
	s_cbranch_vccnz .LBB0_336
	s_ashr_i32 s51, s50, 31
	v_lshl_add_u64 v[72:73], s[50:51], 0, v[0:1]
	v_lshl_add_u64 v[72:73], v[72:73], 2, s[48:49]
	s_waitcnt vmcnt(25)
	v_mov_b32_e32 v69, v102
	v_mul_f32_e32 v69, v76, v69
	v_mul_f32_e32 v67, v67, v69
.LBB0_336:
	s_and_b64 vcc, exec, s[8:9]
	ds_write_b32 v12, v67 offset:1584
	s_cbranch_vccnz .LBB0_338
	s_ashr_i32 s51, s50, 31
	v_lshl_add_u64 v[72:73], s[50:51], 0, v[0:1]
	v_lshl_add_u64 v[72:73], v[72:73], 2, s[48:49]
	s_waitcnt vmcnt(24)
	v_mov_b32_e32 v67, v103
	v_mul_f32_e32 v67, v76, v67
	v_mul_f32_e32 v57, v57, v67
.LBB0_338:
	s_and_b64 vcc, exec, s[8:9]
	ds_write_b32 v12, v57 offset:1848
	s_cbranch_vccnz .LBB0_340
	s_ashr_i32 s51, s50, 31
	v_lshl_add_u64 v[72:73], s[50:51], 0, v[0:1]
	v_lshl_add_u64 v[72:73], v[72:73], 2, s[48:49]
	s_waitcnt vmcnt(23)
	v_mov_b32_e32 v57, v104
	v_mul_f32_e32 v57, v76, v57
	v_mul_f32_e32 v70, v70, v57
.LBB0_340:
	s_and_b64 vcc, exec, s[8:9]
	ds_write_b32 v12, v70 offset:2112
	s_cbranch_vccnz .LBB0_342
	s_ashr_i32 s51, s50, 31
	v_lshl_add_u64 v[70:71], s[50:51], 0, v[0:1]
	v_lshl_add_u64 v[70:71], v[70:71], 2, s[48:49]
	s_waitcnt vmcnt(22)
	v_mov_b32_e32 v57, v105
	v_mul_f32_e32 v57, v76, v57
	v_mul_f32_e32 v68, v68, v57
.LBB0_342:
	s_and_b64 vcc, exec, s[8:9]
	ds_write_b32 v12, v68 offset:2376
	s_cbranch_vccnz .LBB0_344
	s_ashr_i32 s51, s50, 31
	v_lshl_add_u64 v[68:69], s[50:51], 0, v[0:1]
	v_lshl_add_u64 v[68:69], v[68:69], 2, s[48:49]
	s_waitcnt vmcnt(21)
	v_mov_b32_e32 v57, v106
	v_mul_f32_e32 v57, v76, v57
	v_mul_f32_e32 v58, v58, v57
.LBB0_344:
	s_and_b64 vcc, exec, s[8:9]
	ds_write_b32 v12, v58 offset:2640
	s_cbranch_vccnz .LBB0_346
	s_ashr_i32 s51, s50, 31
	v_lshl_add_u64 v[68:69], s[50:51], 0, v[0:1]
	v_lshl_add_u64 v[68:69], v[68:69], 2, s[48:49]
	s_waitcnt vmcnt(20)
	v_mov_b32_e32 v57, v107
	v_mul_f32_e32 v57, v76, v57
	v_mul_f32_e32 v56, v56, v57
.LBB0_346:
	s_and_b64 vcc, exec, s[8:9]
	ds_write_b32 v12, v56 offset:2904
	s_cbranch_vccnz .LBB0_348
	s_ashr_i32 s51, s50, 31
	v_lshl_add_u64 v[56:57], s[50:51], 0, v[0:1]
	v_lshl_add_u64 v[56:57], v[56:57], 2, s[48:49]
	s_waitcnt vmcnt(19)
	v_mov_b32_e32 v56, v108
	v_mul_f32_e32 v56, v76, v56
	v_mul_f32_e32 v55, v55, v56
.LBB0_348:
	s_and_b64 vcc, exec, s[8:9]
	ds_write_b32 v12, v55 offset:3168
	s_cbranch_vccnz .LBB0_350
	s_ashr_i32 s51, s50, 31
	v_lshl_add_u64 v[56:57], s[50:51], 0, v[0:1]
	v_lshl_add_u64 v[56:57], v[56:57], 2, s[48:49]
	s_waitcnt vmcnt(18)
	v_mov_b32_e32 v55, v109
	v_mul_f32_e32 v55, v76, v55
	v_mul_f32_e32 v45, v45, v55
.LBB0_350:
	s_and_b64 vcc, exec, s[8:9]
	ds_write_b32 v12, v45 offset:3432
	s_cbranch_vccnz .LBB0_352
	s_ashr_i32 s51, s50, 31
	v_lshl_add_u64 v[56:57], s[50:51], 0, v[0:1]
	v_lshl_add_u64 v[56:57], v[56:57], 2, s[48:49]
	s_waitcnt vmcnt(17)
	v_mov_b32_e32 v45, v110
	v_mul_f32_e32 v45, v76, v45
	v_mul_f32_e32 v43, v43, v45
.LBB0_352:
	s_and_b64 vcc, exec, s[8:9]
	ds_write_b32 v12, v43 offset:3696
	s_cbranch_vccnz .LBB0_354
	s_ashr_i32 s51, s50, 31
	v_lshl_add_u64 v[56:57], s[50:51], 0, v[0:1]
	v_lshl_add_u64 v[56:57], v[56:57], 2, s[48:49]
	s_waitcnt vmcnt(16)
	v_mov_b32_e32 v43, v111
	v_mul_f32_e32 v43, v76, v43
	v_mul_f32_e32 v41, v41, v43
.LBB0_354:
	s_and_b64 vcc, exec, s[8:9]
	ds_write_b32 v12, v41 offset:3960
	s_cbranch_vccnz .LBB0_356
	s_ashr_i32 s51, s50, 31
	v_lshl_add_u64 v[56:57], s[50:51], 0, v[0:1]
	v_lshl_add_u64 v[56:57], v[56:57], 2, s[48:49]
	s_waitcnt vmcnt(15)
	v_mov_b32_e32 v41, v112
	v_mul_f32_e32 v41, v76, v41
	v_mul_f32_e32 v46, v46, v41
.LBB0_356:
	s_and_b64 vcc, exec, s[8:9]
	ds_write_b32 v12, v46 offset:4224
	s_cbranch_vccnz .LBB0_358
	s_ashr_i32 s51, s50, 31
	v_lshl_add_u64 v[56:57], s[50:51], 0, v[0:1]
	v_lshl_add_u64 v[56:57], v[56:57], 2, s[48:49]
	s_waitcnt vmcnt(14)
	v_mov_b32_e32 v41, v113
	v_mul_f32_e32 v41, v76, v41
	v_mul_f32_e32 v44, v44, v41
.LBB0_358:
	s_and_b64 vcc, exec, s[8:9]
	ds_write_b32 v12, v44 offset:4488
	s_cbranch_vccnz .LBB0_360
	s_ashr_i32 s51, s50, 31
	v_lshl_add_u64 v[44:45], s[50:51], 0, v[0:1]
	v_lshl_add_u64 v[44:45], v[44:45], 2, s[48:49]
	s_waitcnt vmcnt(13)
	v_mov_b32_e32 v41, v114
	v_mul_f32_e32 v41, v76, v41
	v_mul_f32_e32 v42, v42, v41
.LBB0_360:
	s_and_b64 vcc, exec, s[8:9]
	ds_write_b32 v12, v42 offset:4752
	s_cbranch_vccnz .LBB0_362
	s_ashr_i32 s51, s50, 31
	v_lshl_add_u64 v[42:43], s[50:51], 0, v[0:1]
	v_lshl_add_u64 v[42:43], v[42:43], 2, s[48:49]
	s_waitcnt vmcnt(12)
	v_mov_b32_e32 v41, v115
	v_mul_f32_e32 v41, v76, v41
	v_mul_f32_e32 v40, v40, v41
.LBB0_362:
	s_and_b64 vcc, exec, s[8:9]
	ds_write_b32 v12, v40 offset:5016
	s_cbranch_vccnz .LBB0_364
	s_ashr_i32 s51, s50, 31
	v_lshl_add_u64 v[40:41], s[50:51], 0, v[0:1]
	v_lshl_add_u64 v[40:41], v[40:41], 2, s[48:49]
	s_waitcnt vmcnt(11)
	v_mov_b32_e32 v40, v116
	v_mul_f32_e32 v40, v76, v40
	v_mul_f32_e32 v31, v31, v40
.LBB0_364:
	s_and_b64 vcc, exec, s[8:9]
	ds_write_b32 v12, v31 offset:5280
	s_cbranch_vccnz .LBB0_366
	s_ashr_i32 s51, s50, 31
	v_lshl_add_u64 v[40:41], s[50:51], 0, v[0:1]
	v_lshl_add_u64 v[40:41], v[40:41], 2, s[48:49]
	s_waitcnt vmcnt(10)
	v_mov_b32_e32 v31, v117
	v_mul_f32_e32 v31, v76, v31
	v_mul_f32_e32 v29, v29, v31
.LBB0_366:
	s_and_b64 vcc, exec, s[8:9]
	ds_write_b32 v12, v29 offset:5544
	s_cbranch_vccnz .LBB0_368
	s_ashr_i32 s51, s50, 31
	v_lshl_add_u64 v[40:41], s[50:51], 0, v[0:1]
	v_lshl_add_u64 v[40:41], v[40:41], 2, s[48:49]
	s_waitcnt vmcnt(9)
	v_mov_b32_e32 v29, v118
	v_mul_f32_e32 v29, v76, v29
	v_mul_f32_e32 v27, v27, v29
.LBB0_368:
	s_and_b64 vcc, exec, s[8:9]
	ds_write_b32 v12, v27 offset:5808
	s_cbranch_vccnz .LBB0_370
	s_ashr_i32 s51, s50, 31
	v_lshl_add_u64 v[40:41], s[50:51], 0, v[0:1]
	v_lshl_add_u64 v[40:41], v[40:41], 2, s[48:49]
	s_waitcnt vmcnt(8)
	v_mov_b32_e32 v27, v119
	v_mul_f32_e32 v27, v76, v27
	v_mul_f32_e32 v18, v18, v27
.LBB0_370:
	s_and_b64 vcc, exec, s[8:9]
	ds_write_b32 v12, v18 offset:6072
	s_cbranch_vccnz .LBB0_372
	s_ashr_i32 s51, s50, 31
	v_lshl_add_u64 v[40:41], s[50:51], 0, v[0:1]
	v_lshl_add_u64 v[40:41], v[40:41], 2, s[48:49]
	s_waitcnt vmcnt(7)
	v_mov_b32_e32 v18, v120
	v_mul_f32_e32 v18, v76, v18
	v_mul_f32_e32 v30, v30, v18
.LBB0_372:
	s_and_b64 vcc, exec, s[8:9]
	ds_write_b32 v12, v30 offset:6336
	s_cbranch_vccnz .LBB0_374
	s_ashr_i32 s51, s50, 31
	v_lshl_add_u64 v[30:31], s[50:51], 0, v[0:1]
	v_lshl_add_u64 v[30:31], v[30:31], 2, s[48:49]
	s_waitcnt vmcnt(6)
	v_mov_b32_e32 v18, v121
	v_mul_f32_e32 v18, v76, v18
	v_mul_f32_e32 v28, v28, v18
.LBB0_374:
	s_and_b64 vcc, exec, s[8:9]
	ds_write_b32 v12, v28 offset:6600
	s_cbranch_vccnz .LBB0_376
	s_ashr_i32 s51, s50, 31
	v_lshl_add_u64 v[28:29], s[50:51], 0, v[0:1]
	v_lshl_add_u64 v[28:29], v[28:29], 2, s[48:49]
	s_waitcnt vmcnt(5)
	v_mov_b32_e32 v18, v122
	v_mul_f32_e32 v18, v76, v18
	v_mul_f32_e32 v19, v19, v18
.LBB0_376:
	s_and_b64 vcc, exec, s[8:9]
	ds_write_b32 v12, v19 offset:6864
	s_cbranch_vccnz .LBB0_378
	s_ashr_i32 s51, s50, 31
	v_lshl_add_u64 v[18:19], s[50:51], 0, v[0:1]
	v_lshl_add_u64 v[18:19], v[18:19], 2, s[48:49]
	s_waitcnt vmcnt(4)
	v_mov_b32_e32 v18, v123
	v_mul_f32_e32 v18, v76, v18
	v_mul_f32_e32 v17, v17, v18
.LBB0_378:
	s_and_b64 vcc, exec, s[8:9]
	ds_write_b32 v12, v17 offset:7128
	s_cbranch_vccnz .LBB0_380
	s_ashr_i32 s51, s50, 31
	v_lshl_add_u64 v[18:19], s[50:51], 0, v[0:1]
	v_lshl_add_u64 v[18:19], v[18:19], 2, s[48:49]
	s_waitcnt vmcnt(3)
	v_mov_b32_e32 v17, v124
	v_mul_f32_e32 v17, v76, v17
	v_mul_f32_e32 v16, v16, v17
.LBB0_380:
	s_and_b64 vcc, exec, s[8:9]
	ds_write_b32 v12, v16 offset:7392
	s_cbranch_vccnz .LBB0_382
	s_ashr_i32 s51, s50, 31
	v_lshl_add_u64 v[16:17], s[50:51], 0, v[0:1]
	v_lshl_add_u64 v[16:17], v[16:17], 2, s[48:49]
	s_waitcnt vmcnt(2)
	v_mov_b32_e32 v16, v125
	v_mul_f32_e32 v16, v76, v16
	v_mul_f32_e32 v15, v15, v16
.LBB0_382:
	s_and_b64 vcc, exec, s[8:9]
	ds_write_b32 v12, v15 offset:7656
	s_cbranch_vccnz .LBB0_384
	s_ashr_i32 s51, s50, 31
	v_lshl_add_u64 v[16:17], s[50:51], 0, v[0:1]
	v_lshl_add_u64 v[16:17], v[16:17], 2, s[48:49]
	s_waitcnt vmcnt(1)
	v_mov_b32_e32 v15, v126
	v_mul_f32_e32 v15, v76, v15
	v_mul_f32_e32 v14, v14, v15
.LBB0_384:
	s_and_b64 vcc, exec, s[8:9]
	ds_write_b32 v12, v14 offset:7920
	s_cbranch_vccnz .LBB0_386
	s_ashr_i32 s51, s50, 31
	v_lshl_add_u64 v[14:15], s[50:51], 0, v[0:1]
	v_lshl_add_u64 v[14:15], v[14:15], 2, s[48:49]
	s_waitcnt vmcnt(0)
	v_mov_b32_e32 v14, v127
	v_mul_f32_e32 v14, v76, v14
	v_mul_f32_e32 v13, v13, v14

.LBB0_482:
	s_lshl_b32 s22, s56, 1
	s_add_i32 s63, s26, s27
	v_add_u32_e32 v0, s22, v242
	s_add_i32 s22, s63, -5
	v_cvt_f32_i32_e32 v99, s22
	ds_read_b64_tr_b16 v[204:205], v0 offset:24576
	ds_read_b64_tr_b16 v[206:207], v0 offset:25088
	v_lshrrev_b32_e32 v99, 16, v99
	v_cndmask_b32_e64 v99, 0, v99, s[8:9]
	v_mov_b32_e32 v100, v240
	v_lshlrev_b32_e32 v101, 16, v99
	v_or_b32_e32 v142, v101, v99
	v_lshl_or_b32 v140, v100, 16, v100
	v_or_b32_e32 v141, v100, v101
	v_add_f32_e32 v99, v82, v83
	v_add_f32_e32 v99, v84, v99
	v_mfma_f32_32x32x16_bf16 v[116:131], v[140:143], v[136:139], 0
	v_add_f32_e32 v99, v85, v99
	v_add_f32_e32 v99, v86, v99
	v_add_f32_e32 v99, v87, v99
	v_cvt_pk_bf16_f32 v168, v82, v83
	v_cvt_pk_bf16_f32 v169, v84, v85
	s_waitcnt lgkmcnt(9)
	v_mfma_f32_32x32x16_bf16 v[116:131], v[200:203], v[160:163], v[116:131]
	ds_read_b64_tr_b16 v[82:83], v0 offset:28672
	ds_read_b64_tr_b16 v[84:85], v0 offset:29184
	v_mov_b32_e32 v100, v239
	v_add_f32_e32 v99, v88, v99
	v_lshl_or_b32 v140, v100, 16, v100
	v_or_b32_e32 v141, v100, v101
	v_add_f32_e32 v99, v89, v99
	v_add_f32_e32 v99, v90, v99
	v_mfma_f32_32x32x16_bf16 v[100:115], v[140:143], v[136:139], 0
	v_add_f32_e32 v99, v91, v99
	v_cvt_pk_bf16_f32 v170, v86, v87
	v_cvt_pk_bf16_f32 v171, v88, v89
	s_waitcnt lgkmcnt(10)
	v_mfma_f32_32x32x16_bf16 v[100:115], v[196:199], v[160:163], v[100:115]
	ds_read_b64_tr_b16 v[86:87], v0 offset:32768
	ds_read_b64_tr_b16 v[88:89], v0 offset:33280
	s_waitcnt lgkmcnt(11)
	v_mfma_f32_32x32x16_bf16 v[116:131], v[192:195], v[152:155], v[116:131]
	v_add_f32_e32 v99, v92, v99
	v_add_f32_e32 v99, v93, v99
	v_add_f32_e32 v99, v94, v99
	v_add_f32_e32 v99, v95, v99
	v_cvt_pk_bf16_f32 v164, v90, v91
	v_cvt_pk_bf16_f32 v165, v92, v93
	ds_read_b64_tr_b16 v[90:91], v0 offset:36864
	ds_read_b64_tr_b16 v[92:93], v0 offset:37376
	s_waitcnt lgkmcnt(12)
	v_mfma_f32_32x32x16_bf16 v[100:115], v[188:191], v[152:155], v[100:115]
	v_add_f32_e32 v99, v96, v99
	v_add_f32_e32 v99, v97, v99
	v_add_f32_e32 v99, v66, v99
	v_add_f32_e32 v99, v67, v99
	v_cvt_pk_bf16_f32 v166, v94, v95
	v_cvt_pk_bf16_f32 v167, v96, v97
	ds_read_b64_tr_b16 v[94:95], v0 offset:25600
	ds_read_b64_tr_b16 v[96:97], v0 offset:26112
	s_waitcnt lgkmcnt(13)
	v_mfma_f32_32x32x16_bf16 v[116:131], v[184:187], v[148:151], v[116:131]
	v_add_f32_e32 v99, v68, v99
	v_add_f32_e32 v99, v69, v99
	v_add_f32_e32 v99, v70, v99
	v_add_f32_e32 v99, v71, v99
	v_cvt_pk_bf16_f32 v156, v66, v67
	v_cvt_pk_bf16_f32 v157, v68, v69
	ds_read_b64_tr_b16 v[66:67], v0 offset:29696
	ds_read_b64_tr_b16 v[68:69], v0 offset:30208
	s_waitcnt lgkmcnt(14)
	v_mfma_f32_32x32x16_bf16 v[100:115], v[180:183], v[148:151], v[100:115]
	v_add_f32_e32 v99, v72, v99
	v_add_f32_e32 v99, v73, v99
	v_add_f32_e32 v99, v74, v99
	v_add_f32_e32 v99, v75, v99
	v_cvt_pk_bf16_f32 v158, v70, v71
	v_cvt_pk_bf16_f32 v159, v72, v73
	ds_read_b64_tr_b16 v[70:71], v0 offset:33792
	ds_read_b64_tr_b16 v[72:73], v0 offset:34304
	s_waitcnt lgkmcnt(14)
	v_mfma_f32_32x32x16_bf16 v[116:131], v[176:179], v[132:135], v[116:131]
	v_add_f32_e32 v99, v76, v99
	v_add_f32_e32 v99, v77, v99
	v_add_f32_e32 v99, v78, v99
	v_add_f32_e32 v99, v79, v99
	v_cvt_pk_bf16_f32 v144, v74, v75
	v_cvt_pk_bf16_f32 v145, v76, v77
	ds_read_b64_tr_b16 v[74:75], v0 offset:37888
	ds_read_b64_tr_b16 v[76:77], v0 offset:38400
	v_mfma_f32_32x32x16_bf16 v[100:115], v[172:175], v[132:135], v[100:115]
	v_add_f32_e32 v99, v80, v99
	v_add_f32_e32 v99, v81, v99
	v_add_f32_e32 v99, 0, v99
	v_cvt_pk_bf16_f32 v146, v78, v79
	v_cvt_pk_bf16_f32 v147, v80, v81
	v_lshl_add_u64 v[208:209], v[216:217], 0, s[12:13]
	v_lshl_add_u64 v[78:79], v[208:209], 0, s[48:49]
	s_add_i32 s22, s62, s92
	v_lshl_add_u64 v[210:211], v[218:219], 0, s[12:13]
	s_mov_b32 s23, m0
	s_mov_b32 m0, s22
	s_nop 0
	global_load_lds_dwordx4 v[78:79], off
	s_mov_b32 m0, s23
	v_lshl_add_u64 v[78:79], v[210:211], 0, s[42:43]
	s_lshl_b32 s22, s61, 1
	v_lshl_add_u64 v[222:223], v[220:221], 0, s[12:13]
	s_add_i32 s23, s22, s93
	s_mov_b32 s56, m0
	s_mov_b32 m0, s23
	s_nop 0
	global_load_lds_dwordx4 v[78:79], off
	s_mov_b32 m0, s56
	v_lshl_add_u64 v[78:79], v[222:223], 0, s[42:43]
	s_add_i32 s22, s22, s94
	s_mov_b32 s23, m0
	s_mov_b32 m0, s22
	s_nop 0
	global_load_lds_dwordx4 v[78:79], off
	s_mov_b32 m0, s23
	s_waitcnt lgkmcnt(14)
	v_mfma_f32_32x32x16_bf16 v[50:65], v[168:171], v[204:207], v[50:65]
	ds_read_b64_tr_b16 v[78:79], v0 offset:26624
	ds_read_b64_tr_b16 v[80:81], v0 offset:27136
	v_max_f32_e32 v253, v117, v117
	v_max_f32_e32 v254, v116, v116
	v_max_f32_e32 v253, v254, v253
	v_max3_f32 v254, v118, v119, v101
	v_max3_f32 v253, v253, v100, v102
	s_waitcnt lgkmcnt(14)
	v_mfma_f32_32x32x16_bf16 v[34:49], v[168:171], v[82:85], v[34:49]
	ds_read_b64_tr_b16 v[82:83], v0 offset:30720
	ds_read_b64_tr_b16 v[84:85], v0 offset:31232
	v_max3_f32 v253, v253, v103, v120
	v_max3_f32 v254, v254, v122, v123
	v_max3_f32 v253, v253, v121, v104
	v_max3_f32 v254, v254, v106, v107
	v_max3_f32 v253, v253, v105, v124
	s_waitcnt lgkmcnt(14)
	v_mfma_f32_32x32x16_bf16 v[18:33], v[168:171], v[86:89], v[18:33]
	ds_read_b64_tr_b16 v[86:87], v0 offset:34816
	ds_read_b64_tr_b16 v[88:89], v0 offset:35328
	v_max3_f32 v254, v254, v126, v127
	v_max3_f32 v253, v253, v125, v108
	v_max3_f32 v254, v254, v110, v111
	v_max3_f32 v253, v253, v109, v128
	v_max3_f32 v254, v254, v130, v131
	s_waitcnt lgkmcnt(14)
	v_mfma_f32_32x32x16_bf16 v[2:17], v[168:171], v[90:93], v[2:17]
	ds_read_b64_tr_b16 v[90:91], v0 offset:38912
	ds_read_b64_tr_b16 v[92:93], v0 offset:39424
	v_max3_f32 v253, v253, v129, v112
	v_max3_f32 v254, v254, v114, v115
	v_max3_f32 v253, v253, v113, v254
	v_mov_b32_e32 v254, v253
	s_nop 1
	v_permlane32_swap_b32_e32 v253, v254
	v_max_f32_e32 v254, v254, v254
	v_max_f32_e32 v253, v253, v253
	v_max_f32_e32 v253, v253, v254
	v_cmp_lt_f32_e32 vcc, s88, v253
	s_cmp_lg_u64 vcc, 0
	v_add_f32_e32 v98, v98, v99
	s_cselect_b64 s[56:57], -1, 0
	s_cbranch_vccnz .LBB0_490
.LBB0_483:
	s_waitcnt lgkmcnt(14)
	v_mfma_f32_32x32x16_bf16 v[50:65], v[164:167], v[94:97], v[50:65]
	v_exp_f32_e32 v124, v124
	v_exp_f32_e32 v125, v125
	v_exp_f32_e32 v116, v116
	ds_read_b64_tr_b16 v[94:95], v0 offset:27648
	ds_read_b64_tr_b16 v[96:97], v0 offset:28160
	s_waitcnt lgkmcnt(14)
	v_mfma_f32_32x32x16_bf16 v[34:49], v[164:167], v[66:69], v[34:49]
	v_exp_f32_e32 v126, v126
	v_exp_f32_e32 v127, v127
	v_exp_f32_e32 v117, v117
	ds_read_b64_tr_b16 v[200:201], v0 offset:31744
	ds_read_b64_tr_b16 v[202:203], v0 offset:32256
	s_waitcnt lgkmcnt(14)
	v_mfma_f32_32x32x16_bf16 v[18:33], v[164:167], v[70:73], v[18:33]
	v_exp_f32_e32 v128, v128
	v_exp_f32_e32 v129, v129
	v_exp_f32_e32 v118, v118
	ds_read_b64_tr_b16 v[70:71], v0 offset:35840
	ds_read_b64_tr_b16 v[72:73], v0 offset:36352
	s_waitcnt lgkmcnt(14)
	v_mfma_f32_32x32x16_bf16 v[2:17], v[164:167], v[74:77], v[2:17]
	v_exp_f32_e32 v130, v130
	v_exp_f32_e32 v131, v131
	v_exp_f32_e32 v119, v119
	ds_read_b64_tr_b16 v[74:75], v0 offset:39936
	ds_read_b64_tr_b16 v[76:77], v0 offset:40448
	v_add_u32_e32 v0, s61, v241
	ds_read_b128 v[66:69], v0
	ds_read_b128 v[196:199], v0 offset:512
	s_waitcnt lgkmcnt(14)
	v_mfma_f32_32x32x16_bf16 v[50:65], v[156:159], v[78:81], v[50:65]
	v_exp_f32_e32 v100, v100
	v_exp_f32_e32 v101, v101
	v_exp_f32_e32 v120, v120
	ds_read_b128 v[192:195], v0 offset:2048
	ds_read_b128 v[188:191], v0 offset:2560
	v_mfma_f32_32x32x16_bf16 v[34:49], v[156:159], v[82:85], v[34:49]
	v_exp_f32_e32 v102, v102
	v_exp_f32_e32 v103, v103
	v_exp_f32_e32 v121, v121
	ds_read_b128 v[184:187], v0 offset:4096
	ds_read_b128 v[180:183], v0 offset:4608
	s_waitcnt lgkmcnt(14)
	v_mfma_f32_32x32x16_bf16 v[18:33], v[156:159], v[86:89], v[18:33]
	v_exp_f32_e32 v104, v104
	v_exp_f32_e32 v105, v105
	v_exp_f32_e32 v122, v122
	ds_read_b128 v[176:179], v0 offset:6144
	ds_read_b128 v[172:175], v0 offset:6656
	v_mfma_f32_32x32x16_bf16 v[2:17], v[156:159], v[90:93], v[2:17]
	v_exp_f32_e32 v106, v106
	v_exp_f32_e32 v107, v107
	v_exp_f32_e32 v123, v123
	s_waitcnt lgkmcnt(14)
	v_mfma_f32_32x32x16_bf16 v[50:65], v[144:147], v[94:97], v[50:65]
	v_exp_f32_e32 v108, v108
	v_exp_f32_e32 v109, v109
	s_waitcnt lgkmcnt(12)
	v_mfma_f32_32x32x16_bf16 v[34:49], v[144:147], v[200:203], v[34:49]
	v_exp_f32_e32 v110, v110
	v_exp_f32_e32 v111, v111
	s_waitcnt lgkmcnt(10)
	v_mfma_f32_32x32x16_bf16 v[18:33], v[144:147], v[70:73], v[18:33]
	v_exp_f32_e32 v112, v112
	v_exp_f32_e32 v113, v113
	s_waitcnt lgkmcnt(8)
	v_mfma_f32_32x32x16_bf16 v[2:17], v[144:147], v[74:77], v[2:17]
	v_exp_f32_e32 v114, v114
	v_exp_f32_e32 v115, v115
	s_waitcnt vmcnt(3) lgkmcnt(0)
	s_barrier
	s_andn2_b64 vcc, exec, s[56:57]
	v_add_u32_e32 v0, s91, v244
	s_cbranch_vccnz .LBB0_485
	s_waitcnt lgkmcnt(0)
	ds_read_b128 v[70:73], v0 offset:96
	ds_read_b128 v[74:77], v0 offset:64
	ds_read_b128 v[78:81], v0 offset:32
	ds_read_b128 v[82:85], v0
	s_waitcnt lgkmcnt(3)
	v_pk_mul_f32 v[62:63], v[62:63], v[70:71]
	s_waitcnt lgkmcnt(2)
	v_pk_mul_f32 v[58:59], v[58:59], v[74:75]
	s_waitcnt lgkmcnt(1)
	v_pk_mul_f32 v[54:55], v[54:55], v[78:79]
	v_pk_mul_f32 v[64:65], v[64:65], v[72:73]
	v_pk_mul_f32 v[60:61], v[60:61], v[76:77]
	v_pk_mul_f32 v[56:57], v[56:57], v[80:81]
	s_waitcnt lgkmcnt(0)
	v_pk_mul_f32 v[52:53], v[52:53], v[84:85]
	v_pk_mul_f32 v[50:51], v[50:51], v[82:83]
	v_pk_mul_f32 v[46:47], v[46:47], v[70:71]
	v_pk_mul_f32 v[42:43], v[42:43], v[74:75]
	v_pk_mul_f32 v[38:39], v[38:39], v[78:79]
	v_pk_mul_f32 v[48:49], v[48:49], v[72:73]
	v_pk_mul_f32 v[44:45], v[44:45], v[76:77]
	v_pk_mul_f32 v[40:41], v[40:41], v[80:81]
	v_pk_mul_f32 v[36:37], v[36:37], v[84:85]
	v_pk_mul_f32 v[34:35], v[34:35], v[82:83]
	v_pk_mul_f32 v[30:31], v[30:31], v[70:71]
	v_pk_mul_f32 v[26:27], v[26:27], v[74:75]
	v_pk_mul_f32 v[22:23], v[22:23], v[78:79]
	v_pk_mul_f32 v[32:33], v[32:33], v[72:73]
	v_pk_mul_f32 v[28:29], v[28:29], v[76:77]
	v_pk_mul_f32 v[24:25], v[24:25], v[80:81]
	v_pk_mul_f32 v[20:21], v[20:21], v[84:85]
	v_pk_mul_f32 v[18:19], v[18:19], v[82:83]
	v_pk_mul_f32 v[14:15], v[14:15], v[70:71]
	v_pk_mul_f32 v[10:11], v[10:11], v[74:75]
	v_pk_mul_f32 v[6:7], v[6:7], v[78:79]
	v_pk_mul_f32 v[16:17], v[16:17], v[72:73]
	v_pk_mul_f32 v[12:13], v[12:13], v[76:77]
	v_pk_mul_f32 v[8:9], v[8:9], v[80:81]
	v_pk_mul_f32 v[4:5], v[4:5], v[84:85]
	v_pk_mul_f32 v[2:3], v[2:3], v[82:83]
.LBB0_485:
	s_add_i32 s22, s61, 0x2000
	s_cmpk_lg_i32 s61, 0x4000
	s_cselect_b32 s96, s22, 0
	s_lshl_b32 s22, s62, 1
	s_add_i32 s63, s63, -4
	v_add_u32_e32 v99, s22, v242
	v_cvt_f32_i32_e32 v70, s63
	ds_read_b64_tr_b16 v[200:201], v99 offset:24576
	ds_read_b64_tr_b16 v[202:203], v99 offset:25088
	v_lshrrev_b32_e32 v70, 16, v70
	v_cndmask_b32_e64 v70, 0, v70, s[8:9]
	v_mov_b32_e32 v71, v240
	v_lshlrev_b32_e32 v72, 16, v70
	v_or_b32_e32 v142, v72, v70
	v_lshl_or_b32 v140, v71, 16, v71
	v_or_b32_e32 v141, v71, v72
	v_add_f32_e32 v70, v116, v117
	v_cvt_pk_bf16_f32 v168, v116, v117
	v_mfma_f32_32x32x16_bf16 v[82:97], v[140:143], v[136:139], 0
	v_cvt_pk_bf16_f32 v169, v118, v119
	s_waitcnt lgkmcnt(9)
	v_mfma_f32_32x32x16_bf16 v[82:97], v[66:69], v[160:163], v[82:97]
	v_add_f32_e32 v66, v118, v70
	v_add_f32_e32 v66, v119, v66
	v_add_f32_e32 v66, v120, v66
	v_add_f32_e32 v144, v121, v66
	ds_read_b64_tr_b16 v[116:117], v99 offset:28672
	ds_read_b64_tr_b16 v[118:119], v99 offset:29184
	v_mov_b32_e32 v66, v239
	v_cvt_pk_bf16_f32 v170, v120, v121
	v_lshl_or_b32 v140, v66, 16, v66
	v_or_b32_e32 v141, v66, v72
	v_cvt_pk_bf16_f32 v171, v122, v123
	s_nop 0
	v_mfma_f32_32x32x16_bf16 v[66:81], v[140:143], v[136:139], 0
	v_add_f32_e32 v140, v122, v144
	v_add_f32_e32 v140, v123, v140
	v_add_f32_e32 v140, v124, v140
	v_add_f32_e32 v140, v125, v140
	s_waitcnt lgkmcnt(10)
	v_mfma_f32_32x32x16_bf16 v[66:81], v[196:199], v[160:163], v[66:81]
	ds_read_b64_tr_b16 v[120:121], v99 offset:32768
	ds_read_b64_tr_b16 v[122:123], v99 offset:33280
	s_waitcnt lgkmcnt(11)
	v_mfma_f32_32x32x16_bf16 v[82:97], v[192:195], v[152:155], v[82:97]
	v_add_f32_e32 v140, v126, v140
	v_add_f32_e32 v140, v127, v140
	v_add_f32_e32 v140, v128, v140
	v_add_f32_e32 v140, v129, v140
	v_cvt_pk_bf16_f32 v164, v124, v125
	v_cvt_pk_bf16_f32 v165, v126, v127
	ds_read_b64_tr_b16 v[124:125], v99 offset:36864
	ds_read_b64_tr_b16 v[126:127], v99 offset:37376
	s_waitcnt lgkmcnt(12)
	v_mfma_f32_32x32x16_bf16 v[66:81], v[188:191], v[152:155], v[66:81]
	v_add_f32_e32 v140, v130, v140
	v_add_f32_e32 v140, v131, v140
	v_add_f32_e32 v140, v100, v140
	v_add_f32_e32 v140, v101, v140
	v_cvt_pk_bf16_f32 v166, v128, v129
	v_cvt_pk_bf16_f32 v167, v130, v131
	ds_read_b64_tr_b16 v[128:129], v99 offset:25600
	ds_read_b64_tr_b16 v[130:131], v99 offset:26112
	s_waitcnt lgkmcnt(13)
	v_mfma_f32_32x32x16_bf16 v[82:97], v[184:187], v[148:151], v[82:97]
	v_add_f32_e32 v140, v102, v140
	v_add_f32_e32 v140, v103, v140
	v_add_f32_e32 v140, v104, v140
	v_add_f32_e32 v140, v105, v140
	v_cvt_pk_bf16_f32 v156, v100, v101
	v_cvt_pk_bf16_f32 v157, v102, v103
	ds_read_b64_tr_b16 v[100:101], v99 offset:29696
	ds_read_b64_tr_b16 v[102:103], v99 offset:30208
	s_waitcnt lgkmcnt(14)
	v_mfma_f32_32x32x16_bf16 v[66:81], v[180:183], v[148:151], v[66:81]
	v_add_f32_e32 v140, v106, v140
	v_add_f32_e32 v140, v107, v140
	v_add_f32_e32 v140, v108, v140
	v_add_f32_e32 v140, v109, v140
	v_cvt_pk_bf16_f32 v158, v104, v105
	v_cvt_pk_bf16_f32 v159, v106, v107
	ds_read_b64_tr_b16 v[104:105], v99 offset:33792
	ds_read_b64_tr_b16 v[106:107], v99 offset:34304
	s_waitcnt lgkmcnt(14)
	v_mfma_f32_32x32x16_bf16 v[82:97], v[176:179], v[132:135], v[82:97]
	v_add_f32_e32 v140, v110, v140
	v_add_f32_e32 v140, v111, v140
	v_add_f32_e32 v140, v112, v140
	v_add_f32_e32 v140, v113, v140
	v_cvt_pk_bf16_f32 v144, v108, v109
	v_cvt_pk_bf16_f32 v145, v110, v111
	ds_read_b64_tr_b16 v[108:109], v99 offset:37888
	ds_read_b64_tr_b16 v[110:111], v99 offset:38400
	v_mfma_f32_32x32x16_bf16 v[66:81], v[172:175], v[132:135], v[66:81]
	v_add_f32_e32 v140, v114, v140
	v_add_f32_e32 v140, v115, v140
	v_add_f32_e32 v140, 0, v140
	v_cvt_pk_bf16_f32 v146, v112, v113
	v_cvt_pk_bf16_f32 v147, v114, v115
	v_lshl_add_u64 v[112:113], v[208:209], 0, s[50:51]
	s_add_i32 s22, s61, s92
	s_mov_b32 s23, m0
	s_mov_b32 m0, s22
	s_nop 0
	global_load_lds_dwordx4 v[112:113], off
	s_mov_b32 m0, s23
	v_lshl_add_u64 v[112:113], v[210:211], 0, s[44:45]
	s_lshl_b32 s22, s96, 1
	s_add_i32 s23, s22, s93
	s_mov_b32 s56, m0
	s_mov_b32 m0, s23
	s_nop 0
	global_load_lds_dwordx4 v[112:113], off
	s_mov_b32 m0, s56
	v_lshl_add_u64 v[112:113], v[222:223], 0, s[44:45]
	s_add_i32 s22, s22, s94
	s_mov_b32 s23, m0
	s_mov_b32 m0, s22
	s_nop 0
	global_load_lds_dwordx4 v[112:113], off
	s_mov_b32 m0, s23
	s_waitcnt lgkmcnt(14)
	v_mfma_f32_32x32x16_bf16 v[50:65], v[168:171], v[200:203], v[50:65]
	ds_read_b64_tr_b16 v[112:113], v99 offset:26624
	ds_read_b64_tr_b16 v[114:115], v99 offset:27136
	v_max_f32_e32 v253, v83, v83
	v_max_f32_e32 v254, v82, v82
	v_max_f32_e32 v253, v254, v253
	v_max3_f32 v254, v84, v85, v67
	v_max3_f32 v253, v253, v66, v68
	s_waitcnt lgkmcnt(14)
	v_mfma_f32_32x32x16_bf16 v[34:49], v[168:171], v[116:119], v[34:49]
	ds_read_b64_tr_b16 v[116:117], v99 offset:30720
	ds_read_b64_tr_b16 v[118:119], v99 offset:31232
	v_max3_f32 v253, v253, v69, v86
	v_max3_f32 v254, v254, v88, v89
	v_max3_f32 v253, v253, v87, v70
	v_max3_f32 v254, v254, v72, v73
	v_max3_f32 v253, v253, v71, v90
	s_waitcnt lgkmcnt(14)
	v_mfma_f32_32x32x16_bf16 v[18:33], v[168:171], v[120:123], v[18:33]
	ds_read_b64_tr_b16 v[120:121], v99 offset:34816
	ds_read_b64_tr_b16 v[122:123], v99 offset:35328
	v_max3_f32 v254, v254, v92, v93
	v_max3_f32 v253, v253, v91, v74
	v_max3_f32 v254, v254, v76, v77
	v_max3_f32 v253, v253, v75, v94
	v_max3_f32 v254, v254, v96, v97
	s_waitcnt lgkmcnt(14)
	v_mfma_f32_32x32x16_bf16 v[2:17], v[168:171], v[124:127], v[2:17]
	ds_read_b64_tr_b16 v[124:125], v99 offset:38912
	ds_read_b64_tr_b16 v[126:127], v99 offset:39424
	v_max3_f32 v253, v253, v95, v78
	v_max3_f32 v254, v254, v80, v81
	v_max3_f32 v253, v253, v79, v254
	v_mov_b32_e32 v254, v253
	s_nop 1
	v_permlane32_swap_b32_e32 v253, v254
	v_max_f32_e32 v254, v254, v254
	v_max_f32_e32 v253, v253, v253
	v_max_f32_e32 v253, v253, v254
	v_cmp_lt_f32_e32 vcc, s88, v253
	s_cmp_lg_u64 vcc, 0
	v_add_f32_e32 v98, v98, v140
	s_cselect_b64 s[56:57], -1, 0
	s_cbranch_vccnz .LBB0_493
.LBB0_486:
	s_waitcnt lgkmcnt(14)
	v_mfma_f32_32x32x16_bf16 v[50:65], v[164:167], v[128:131], v[50:65]
	v_exp_f32_e32 v90, v90
	v_exp_f32_e32 v91, v91
	v_exp_f32_e32 v82, v82
	ds_read_b64_tr_b16 v[128:129], v99 offset:27648
	ds_read_b64_tr_b16 v[130:131], v99 offset:28160
	s_waitcnt lgkmcnt(14)
	v_mfma_f32_32x32x16_bf16 v[34:49], v[164:167], v[100:103], v[34:49]
	v_exp_f32_e32 v92, v92
	v_exp_f32_e32 v93, v93
	v_exp_f32_e32 v83, v83
	ds_read_b64_tr_b16 v[100:101], v99 offset:31744
	ds_read_b64_tr_b16 v[102:103], v99 offset:32256
	s_waitcnt lgkmcnt(14)
	v_mfma_f32_32x32x16_bf16 v[18:33], v[164:167], v[104:107], v[18:33]
	v_exp_f32_e32 v94, v94
	v_exp_f32_e32 v95, v95
	v_exp_f32_e32 v84, v84
	ds_read_b64_tr_b16 v[104:105], v99 offset:35840
	ds_read_b64_tr_b16 v[106:107], v99 offset:36352
	s_waitcnt lgkmcnt(14)
	v_mfma_f32_32x32x16_bf16 v[2:17], v[164:167], v[108:111], v[2:17]
	v_exp_f32_e32 v96, v96
	v_exp_f32_e32 v97, v97
	v_exp_f32_e32 v85, v85
	ds_read_b64_tr_b16 v[108:109], v99 offset:39936
	ds_read_b64_tr_b16 v[110:111], v99 offset:40448
	v_add_u32_e32 v99, s96, v241
	ds_read_b128 v[200:203], v99
	ds_read_b128 v[196:199], v99 offset:512
	s_waitcnt lgkmcnt(14)
	v_mfma_f32_32x32x16_bf16 v[50:65], v[156:159], v[112:115], v[50:65]
	v_exp_f32_e32 v66, v66
	v_exp_f32_e32 v67, v67
	v_exp_f32_e32 v86, v86
	ds_read_b128 v[192:195], v99 offset:2048
	ds_read_b128 v[188:191], v99 offset:2560
	v_mfma_f32_32x32x16_bf16 v[34:49], v[156:159], v[116:119], v[34:49]
	v_exp_f32_e32 v68, v68
	v_exp_f32_e32 v69, v69
	v_exp_f32_e32 v87, v87
	ds_read_b128 v[184:187], v99 offset:4096
	ds_read_b128 v[180:183], v99 offset:4608
	s_waitcnt lgkmcnt(14)
	v_mfma_f32_32x32x16_bf16 v[18:33], v[156:159], v[120:123], v[18:33]
	v_exp_f32_e32 v70, v70
	v_exp_f32_e32 v71, v71
	v_exp_f32_e32 v88, v88
	ds_read_b128 v[176:179], v99 offset:6144
	ds_read_b128 v[172:175], v99 offset:6656
	v_mfma_f32_32x32x16_bf16 v[2:17], v[156:159], v[124:127], v[2:17]
	v_exp_f32_e32 v72, v72
	v_exp_f32_e32 v73, v73
	v_exp_f32_e32 v89, v89
	s_waitcnt lgkmcnt(14)
	v_mfma_f32_32x32x16_bf16 v[50:65], v[144:147], v[128:131], v[50:65]
	v_exp_f32_e32 v74, v74
	v_exp_f32_e32 v75, v75
	s_waitcnt lgkmcnt(12)
	v_mfma_f32_32x32x16_bf16 v[34:49], v[144:147], v[100:103], v[34:49]
	v_exp_f32_e32 v76, v76
	v_exp_f32_e32 v77, v77
	s_waitcnt lgkmcnt(10)
	v_mfma_f32_32x32x16_bf16 v[18:33], v[144:147], v[104:107], v[18:33]
	v_exp_f32_e32 v78, v78
	v_exp_f32_e32 v79, v79
	s_waitcnt lgkmcnt(8)
	v_mfma_f32_32x32x16_bf16 v[2:17], v[144:147], v[108:111], v[2:17]
	v_exp_f32_e32 v80, v80
	v_exp_f32_e32 v81, v81
	s_waitcnt vmcnt(3) lgkmcnt(0)
	s_barrier
	s_andn2_b64 vcc, exec, s[56:57]
	s_cbranch_vccnz .LBB0_488
	s_waitcnt lgkmcnt(0)
	ds_read_b128 v[100:103], v0 offset:96
	ds_read_b128 v[104:107], v0 offset:64
	ds_read_b128 v[108:111], v0 offset:32
	ds_read_b128 v[112:115], v0
	s_waitcnt lgkmcnt(3)
	v_pk_mul_f32 v[62:63], v[62:63], v[100:101]
	s_waitcnt lgkmcnt(2)
	v_pk_mul_f32 v[58:59], v[58:59], v[104:105]
	s_waitcnt lgkmcnt(1)
	v_pk_mul_f32 v[54:55], v[54:55], v[108:109]
	v_pk_mul_f32 v[64:65], v[64:65], v[102:103]
	v_pk_mul_f32 v[60:61], v[60:61], v[106:107]
	v_pk_mul_f32 v[56:57], v[56:57], v[110:111]
	s_waitcnt lgkmcnt(0)
	v_pk_mul_f32 v[52:53], v[52:53], v[114:115]
	v_pk_mul_f32 v[50:51], v[50:51], v[112:113]
	v_pk_mul_f32 v[46:47], v[46:47], v[100:101]
	v_pk_mul_f32 v[42:43], v[42:43], v[104:105]
	v_pk_mul_f32 v[38:39], v[38:39], v[108:109]
	v_pk_mul_f32 v[48:49], v[48:49], v[102:103]
	v_pk_mul_f32 v[44:45], v[44:45], v[106:107]
	v_pk_mul_f32 v[40:41], v[40:41], v[110:111]
	v_pk_mul_f32 v[36:37], v[36:37], v[114:115]
	v_pk_mul_f32 v[34:35], v[34:35], v[112:113]
	v_pk_mul_f32 v[30:31], v[30:31], v[100:101]
	v_pk_mul_f32 v[26:27], v[26:27], v[104:105]
	v_pk_mul_f32 v[22:23], v[22:23], v[108:109]
	v_pk_mul_f32 v[32:33], v[32:33], v[102:103]
	v_pk_mul_f32 v[28:29], v[28:29], v[106:107]
	v_pk_mul_f32 v[24:25], v[24:25], v[110:111]
	v_pk_mul_f32 v[20:21], v[20:21], v[114:115]
	v_pk_mul_f32 v[18:19], v[18:19], v[112:113]
	v_pk_mul_f32 v[14:15], v[14:15], v[100:101]
	v_pk_mul_f32 v[10:11], v[10:11], v[104:105]
	v_pk_mul_f32 v[6:7], v[6:7], v[108:109]
	v_pk_mul_f32 v[16:17], v[16:17], v[102:103]
	v_pk_mul_f32 v[12:13], v[12:13], v[106:107]
	v_pk_mul_f32 v[8:9], v[8:9], v[110:111]
	v_pk_mul_f32 v[4:5], v[4:5], v[114:115]
	v_pk_mul_f32 v[2:3], v[2:3], v[112:113]

.LBB0_490:
	v_max_f32_e32 v253, v253, v253
	v_max_f32_e32 v253, 0, v253
	v_ceil_f32_e32 v254, v253
	v_exp_f32_e64 v253, -v254
	s_and_saveexec_b64 s[58:59], s[8:9]
	ds_write_b32 v237, v253
	s_or_b64 exec, exec, s[58:59]
	v_add_f32_e32 v243, v243, v254
	v_sub_f32_e32 v131, v131, v254
	v_sub_f32_e32 v130, v130, v254
	v_sub_f32_e32 v129, v129, v254
	v_sub_f32_e32 v128, v128, v254
	v_sub_f32_e32 v127, v127, v254
	v_sub_f32_e32 v126, v126, v254
	v_sub_f32_e32 v125, v125, v254
	v_sub_f32_e32 v124, v124, v254
	v_sub_f32_e32 v123, v123, v254
	v_sub_f32_e32 v122, v122, v254
	v_sub_f32_e32 v121, v121, v254
	v_sub_f32_e32 v120, v120, v254
	v_sub_f32_e32 v119, v119, v254
	v_sub_f32_e32 v118, v118, v254
	v_sub_f32_e32 v117, v117, v254
	v_sub_f32_e32 v116, v116, v254
	v_sub_f32_e32 v115, v115, v254
	v_sub_f32_e32 v114, v114, v254
	v_sub_f32_e32 v113, v113, v254
	v_sub_f32_e32 v112, v112, v254
	v_sub_f32_e32 v111, v111, v254
	v_sub_f32_e32 v110, v110, v254
	v_sub_f32_e32 v109, v109, v254
	v_sub_f32_e32 v108, v108, v254
	v_sub_f32_e32 v107, v107, v254
	v_sub_f32_e32 v106, v106, v254
	v_sub_f32_e32 v105, v105, v254
	v_sub_f32_e32 v104, v104, v254
	v_sub_f32_e32 v103, v103, v254
	v_sub_f32_e32 v102, v102, v254
	v_sub_f32_e32 v101, v101, v254
	v_sub_f32_e32 v100, v100, v254
	v_bfe_u32 v254, v243, 16, 1
	v_add3_u32 v254, v243, v254, s84
	v_and_b32_e32 v254, 0xffff0000, v254
	v_sub_f32_e32 v255, v243, v254
	v_xor_b32_e32 v254, 0x80000000, v254
	v_lshrrev_b32_e32 v254, 16, v254
	v_xor_b32_e32 v255, 0x80000000, v255
	v_and_or_b32 v254, v255, s85, v254
	v_cndmask_b32_e64 v139, 0, v254, s[8:9]
	v_mul_f32_e32 v98, v98, v253
	s_branch .LBB0_483
.LBB0_493:
	v_max_f32_e32 v253, v253, v253
	v_max_f32_e32 v253, 0, v253
	v_ceil_f32_e32 v254, v253
	v_exp_f32_e64 v253, -v254
	s_and_saveexec_b64 s[58:59], s[8:9]
	ds_write_b32 v237, v253
	s_or_b64 exec, exec, s[58:59]
	v_add_f32_e32 v243, v243, v254
	v_sub_f32_e32 v97, v97, v254
	v_sub_f32_e32 v96, v96, v254
	v_sub_f32_e32 v95, v95, v254
	v_sub_f32_e32 v94, v94, v254
	v_sub_f32_e32 v93, v93, v254
	v_sub_f32_e32 v92, v92, v254
	v_sub_f32_e32 v91, v91, v254
	v_sub_f32_e32 v90, v90, v254
	v_sub_f32_e32 v89, v89, v254
	v_sub_f32_e32 v88, v88, v254
	v_sub_f32_e32 v87, v87, v254
	v_sub_f32_e32 v86, v86, v254
	v_sub_f32_e32 v85, v85, v254
	v_sub_f32_e32 v84, v84, v254
	v_sub_f32_e32 v83, v83, v254
	v_sub_f32_e32 v82, v82, v254
	v_sub_f32_e32 v81, v81, v254
	v_sub_f32_e32 v80, v80, v254
	v_sub_f32_e32 v79, v79, v254
	v_sub_f32_e32 v78, v78, v254
	v_sub_f32_e32 v77, v77, v254
	v_sub_f32_e32 v76, v76, v254
	v_sub_f32_e32 v75, v75, v254
	v_sub_f32_e32 v74, v74, v254
	v_sub_f32_e32 v73, v73, v254
	v_sub_f32_e32 v72, v72, v254
	v_sub_f32_e32 v71, v71, v254
	v_sub_f32_e32 v70, v70, v254
	v_sub_f32_e32 v69, v69, v254
	v_sub_f32_e32 v68, v68, v254
	v_sub_f32_e32 v67, v67, v254
	v_sub_f32_e32 v66, v66, v254
	v_bfe_u32 v254, v243, 16, 1
	v_add3_u32 v254, v243, v254, s84
	v_and_b32_e32 v254, 0xffff0000, v254
	v_sub_f32_e32 v255, v243, v254
	v_xor_b32_e32 v254, 0x80000000, v254
	v_lshrrev_b32_e32 v254, 16, v254
	v_xor_b32_e32 v255, 0x80000000, v255
	v_and_or_b32 v254, v255, s85, v254
	v_cndmask_b32_e64 v139, 0, v254, s[8:9]
	v_mul_f32_e32 v98, v98, v253
	s_branch .LBB0_486

.LBB0_919:
	s_cmp_eq_u32 s26, 1
	s_cselect_b64 s[10:11], -1, 0
	s_cmpk_lt_i32 s42, 0x200
	s_cselect_b64 s[22:23], -1, 0
	s_and_b64 vcc, s[22:23], s[10:11]
	s_cmp_lg_u32 s26, 0
	v_cndmask_b32_e32 v76, 1.0, v11, vcc
	s_cselect_b64 s[56:57], -1, 0
	s_cmp_eq_u32 s26, 0
	s_cbranch_scc1 .LBB0_921
	v_or_b32_e32 v78, s46, v0
	v_ashrrev_i32_e32 v79, 31, v78
	v_lshl_add_u64 v[78:79], v[78:79], 2, s[44:45]
	global_load_dword v96, v[78:79], off
	global_load_dword v97, v[78:79], off offset:8
	global_load_dword v98, v[78:79], off offset:16
	global_load_dword v99, v[78:79], off offset:24
	global_load_dword v100, v[78:79], off offset:32
	global_load_dword v101, v[78:79], off offset:40
	global_load_dword v102, v[78:79], off offset:48
	global_load_dword v103, v[78:79], off offset:56
	global_load_dword v104, v[78:79], off offset:64
	global_load_dword v105, v[78:79], off offset:72
	global_load_dword v106, v[78:79], off offset:80
	global_load_dword v107, v[78:79], off offset:88
	global_load_dword v108, v[78:79], off offset:96
	global_load_dword v109, v[78:79], off offset:104
	global_load_dword v110, v[78:79], off offset:112
	global_load_dword v111, v[78:79], off offset:120
	global_load_dword v112, v[78:79], off offset:128
	global_load_dword v113, v[78:79], off offset:136
	global_load_dword v114, v[78:79], off offset:144
	global_load_dword v115, v[78:79], off offset:152
	global_load_dword v116, v[78:79], off offset:160
	global_load_dword v117, v[78:79], off offset:168
	global_load_dword v118, v[78:79], off offset:176
	global_load_dword v119, v[78:79], off offset:184
	global_load_dword v120, v[78:79], off offset:192
	global_load_dword v121, v[78:79], off offset:200
	global_load_dword v122, v[78:79], off offset:208
	global_load_dword v123, v[78:79], off offset:216
	global_load_dword v124, v[78:79], off offset:224
	global_load_dword v125, v[78:79], off offset:232
	global_load_dword v126, v[78:79], off offset:240
	global_load_dword v127, v[78:79], off offset:248
	s_waitcnt vmcnt(31)
	v_mov_b32_e32 v77, v96
	v_mul_f32_e32 v77, v76, v77
	v_mul_f32_e32 v75, v75, v77
.LBB0_921:
	v_cndmask_b32_e64 v77, 0, 1, s[56:57]
	v_cmp_ne_u32_e64 s[10:11], 1, v77
	s_andn2_b64 vcc, exec, s[56:57]
	s_waitcnt vmcnt(0)
	ds_write_b32 v12, v75
	s_cbranch_vccnz .LBB0_923
	s_ashr_i32 s47, s46, 31
	v_lshl_add_u64 v[78:79], s[46:47], 0, v[0:1]
	v_lshl_add_u64 v[78:79], v[78:79], 2, s[44:45]
	s_waitcnt vmcnt(30)
	v_mov_b32_e32 v75, v97
	v_mul_f32_e32 v75, v76, v75
	v_mul_f32_e32 v74, v74, v75
.LBB0_923:
	s_and_b64 vcc, exec, s[10:11]
	ds_write_b32 v12, v74 offset:264
	s_cbranch_vccnz .LBB0_925
	s_ashr_i32 s47, s46, 31
	v_lshl_add_u64 v[74:75], s[46:47], 0, v[0:1]
	v_lshl_add_u64 v[74:75], v[74:75], 2, s[44:45]
	s_waitcnt vmcnt(29)
	v_mov_b32_e32 v74, v98
	v_mul_f32_e32 v74, v76, v74
	v_mul_f32_e32 v73, v73, v74
.LBB0_925:
	s_and_b64 vcc, exec, s[10:11]
	ds_write_b32 v12, v73 offset:528
	s_cbranch_vccnz .LBB0_927
	s_ashr_i32 s47, s46, 31
	v_lshl_add_u64 v[74:75], s[46:47], 0, v[0:1]
	v_lshl_add_u64 v[74:75], v[74:75], 2, s[44:45]
	s_waitcnt vmcnt(28)
	v_mov_b32_e32 v73, v99
	v_mul_f32_e32 v73, v76, v73
	v_mul_f32_e32 v72, v72, v73
.LBB0_927:
	s_and_b64 vcc, exec, s[10:11]
	ds_write_b32 v12, v72 offset:792
	s_cbranch_vccnz .LBB0_929
	s_ashr_i32 s47, s46, 31
	v_lshl_add_u64 v[72:73], s[46:47], 0, v[0:1]
	v_lshl_add_u64 v[72:73], v[72:73], 2, s[44:45]
	s_waitcnt vmcnt(27)
	v_mov_b32_e32 v72, v100
	v_mul_f32_e32 v72, v76, v72
	v_mul_f32_e32 v71, v71, v72
.LBB0_929:
	s_and_b64 vcc, exec, s[10:11]
	ds_write_b32 v12, v71 offset:1056
	s_cbranch_vccnz .LBB0_931
	s_ashr_i32 s47, s46, 31
	v_lshl_add_u64 v[72:73], s[46:47], 0, v[0:1]
	v_lshl_add_u64 v[72:73], v[72:73], 2, s[44:45]
	s_waitcnt vmcnt(26)
	v_mov_b32_e32 v71, v101
	v_mul_f32_e32 v71, v76, v71
	v_mul_f32_e32 v69, v69, v71
.LBB0_931:
	s_and_b64 vcc, exec, s[10:11]
	ds_write_b32 v12, v69 offset:1320
	s_cbranch_vccnz .LBB0_933
	s_ashr_i32 s47, s46, 31
	v_lshl_add_u64 v[72:73], s[46:47], 0, v[0:1]
	v_lshl_add_u64 v[72:73], v[72:73], 2, s[44:45]
	s_waitcnt vmcnt(25)
	v_mov_b32_e32 v69, v102
	v_mul_f32_e32 v69, v76, v69
	v_mul_f32_e32 v67, v67, v69
.LBB0_933:
	s_and_b64 vcc, exec, s[10:11]
	ds_write_b32 v12, v67 offset:1584
	s_cbranch_vccnz .LBB0_935
	s_ashr_i32 s47, s46, 31
	v_lshl_add_u64 v[72:73], s[46:47], 0, v[0:1]
	v_lshl_add_u64 v[72:73], v[72:73], 2, s[44:45]
	s_waitcnt vmcnt(24)
	v_mov_b32_e32 v67, v103
	v_mul_f32_e32 v67, v76, v67
	v_mul_f32_e32 v57, v57, v67
.LBB0_935:
	s_and_b64 vcc, exec, s[10:11]
	ds_write_b32 v12, v57 offset:1848
	s_cbranch_vccnz .LBB0_937
	s_ashr_i32 s47, s46, 31
	v_lshl_add_u64 v[72:73], s[46:47], 0, v[0:1]
	v_lshl_add_u64 v[72:73], v[72:73], 2, s[44:45]
	s_waitcnt vmcnt(23)
	v_mov_b32_e32 v57, v104
	v_mul_f32_e32 v57, v76, v57
	v_mul_f32_e32 v70, v70, v57
.LBB0_937:
	s_and_b64 vcc, exec, s[10:11]
	ds_write_b32 v12, v70 offset:2112
	s_cbranch_vccnz .LBB0_939
	s_ashr_i32 s47, s46, 31
	v_lshl_add_u64 v[70:71], s[46:47], 0, v[0:1]
	v_lshl_add_u64 v[70:71], v[70:71], 2, s[44:45]
	s_waitcnt vmcnt(22)
	v_mov_b32_e32 v57, v105
	v_mul_f32_e32 v57, v76, v57
	v_mul_f32_e32 v68, v68, v57
.LBB0_939:
	s_and_b64 vcc, exec, s[10:11]
	ds_write_b32 v12, v68 offset:2376
	s_cbranch_vccnz .LBB0_941
	s_ashr_i32 s47, s46, 31
	v_lshl_add_u64 v[68:69], s[46:47], 0, v[0:1]
	v_lshl_add_u64 v[68:69], v[68:69], 2, s[44:45]
	s_waitcnt vmcnt(21)
	v_mov_b32_e32 v57, v106
	v_mul_f32_e32 v57, v76, v57
	v_mul_f32_e32 v58, v58, v57
.LBB0_941:
	s_and_b64 vcc, exec, s[10:11]
	ds_write_b32 v12, v58 offset:2640
	s_cbranch_vccnz .LBB0_943
	s_ashr_i32 s47, s46, 31
	v_lshl_add_u64 v[68:69], s[46:47], 0, v[0:1]
	v_lshl_add_u64 v[68:69], v[68:69], 2, s[44:45]
	s_waitcnt vmcnt(20)
	v_mov_b32_e32 v57, v107
	v_mul_f32_e32 v57, v76, v57
	v_mul_f32_e32 v56, v56, v57
.LBB0_943:
	s_and_b64 vcc, exec, s[10:11]
	ds_write_b32 v12, v56 offset:2904
	s_cbranch_vccnz .LBB0_945
	s_ashr_i32 s47, s46, 31
	v_lshl_add_u64 v[56:57], s[46:47], 0, v[0:1]
	v_lshl_add_u64 v[56:57], v[56:57], 2, s[44:45]
	s_waitcnt vmcnt(19)
	v_mov_b32_e32 v56, v108
	v_mul_f32_e32 v56, v76, v56
	v_mul_f32_e32 v55, v55, v56
.LBB0_945:
	s_and_b64 vcc, exec, s[10:11]
	ds_write_b32 v12, v55 offset:3168
	s_cbranch_vccnz .LBB0_947
	s_ashr_i32 s47, s46, 31
	v_lshl_add_u64 v[56:57], s[46:47], 0, v[0:1]
	v_lshl_add_u64 v[56:57], v[56:57], 2, s[44:45]
	s_waitcnt vmcnt(18)
	v_mov_b32_e32 v55, v109
	v_mul_f32_e32 v55, v76, v55
	v_mul_f32_e32 v45, v45, v55
.LBB0_947:
	s_and_b64 vcc, exec, s[10:11]
	ds_write_b32 v12, v45 offset:3432
	s_cbranch_vccnz .LBB0_949
	s_ashr_i32 s47, s46, 31
	v_lshl_add_u64 v[56:57], s[46:47], 0, v[0:1]
	v_lshl_add_u64 v[56:57], v[56:57], 2, s[44:45]
	s_waitcnt vmcnt(17)
	v_mov_b32_e32 v45, v110
	v_mul_f32_e32 v45, v76, v45
	v_mul_f32_e32 v43, v43, v45
.LBB0_949:
	s_and_b64 vcc, exec, s[10:11]
	ds_write_b32 v12, v43 offset:3696
	s_cbranch_vccnz .LBB0_951
	s_ashr_i32 s47, s46, 31
	v_lshl_add_u64 v[56:57], s[46:47], 0, v[0:1]
	v_lshl_add_u64 v[56:57], v[56:57], 2, s[44:45]
	s_waitcnt vmcnt(16)
	v_mov_b32_e32 v43, v111
	v_mul_f32_e32 v43, v76, v43
	v_mul_f32_e32 v41, v41, v43
.LBB0_951:
	s_and_b64 vcc, exec, s[10:11]
	ds_write_b32 v12, v41 offset:3960
	s_cbranch_vccnz .LBB0_953
	s_ashr_i32 s47, s46, 31
	v_lshl_add_u64 v[56:57], s[46:47], 0, v[0:1]
	v_lshl_add_u64 v[56:57], v[56:57], 2, s[44:45]
	s_waitcnt vmcnt(15)
	v_mov_b32_e32 v41, v112
	v_mul_f32_e32 v41, v76, v41
	v_mul_f32_e32 v46, v46, v41
.LBB0_953:
	s_and_b64 vcc, exec, s[10:11]
	ds_write_b32 v12, v46 offset:4224
	s_cbranch_vccnz .LBB0_955
	s_ashr_i32 s47, s46, 31
	v_lshl_add_u64 v[56:57], s[46:47], 0, v[0:1]
	v_lshl_add_u64 v[56:57], v[56:57], 2, s[44:45]
	s_waitcnt vmcnt(14)
	v_mov_b32_e32 v41, v113
	v_mul_f32_e32 v41, v76, v41
	v_mul_f32_e32 v44, v44, v41
.LBB0_955:
	s_and_b64 vcc, exec, s[10:11]
	ds_write_b32 v12, v44 offset:4488
	s_cbranch_vccnz .LBB0_957
	s_ashr_i32 s47, s46, 31
	v_lshl_add_u64 v[44:45], s[46:47], 0, v[0:1]
	v_lshl_add_u64 v[44:45], v[44:45], 2, s[44:45]
	s_waitcnt vmcnt(13)
	v_mov_b32_e32 v41, v114
	v_mul_f32_e32 v41, v76, v41
	v_mul_f32_e32 v42, v42, v41
.LBB0_957:
	s_and_b64 vcc, exec, s[10:11]
	ds_write_b32 v12, v42 offset:4752
	s_cbranch_vccnz .LBB0_959
	s_ashr_i32 s47, s46, 31
	v_lshl_add_u64 v[42:43], s[46:47], 0, v[0:1]
	v_lshl_add_u64 v[42:43], v[42:43], 2, s[44:45]
	s_waitcnt vmcnt(12)
	v_mov_b32_e32 v41, v115
	v_mul_f32_e32 v41, v76, v41
	v_mul_f32_e32 v40, v40, v41
.LBB0_959:
	s_and_b64 vcc, exec, s[10:11]
	ds_write_b32 v12, v40 offset:5016
	s_cbranch_vccnz .LBB0_961
	s_ashr_i32 s47, s46, 31
	v_lshl_add_u64 v[40:41], s[46:47], 0, v[0:1]
	v_lshl_add_u64 v[40:41], v[40:41], 2, s[44:45]
	s_waitcnt vmcnt(11)
	v_mov_b32_e32 v40, v116
	v_mul_f32_e32 v40, v76, v40
	v_mul_f32_e32 v31, v31, v40
.LBB0_961:
	s_and_b64 vcc, exec, s[10:11]
	ds_write_b32 v12, v31 offset:5280
	s_cbranch_vccnz .LBB0_963
	s_ashr_i32 s47, s46, 31
	v_lshl_add_u64 v[40:41], s[46:47], 0, v[0:1]
	v_lshl_add_u64 v[40:41], v[40:41], 2, s[44:45]
	s_waitcnt vmcnt(10)
	v_mov_b32_e32 v31, v117
	v_mul_f32_e32 v31, v76, v31
	v_mul_f32_e32 v29, v29, v31
.LBB0_963:
	s_and_b64 vcc, exec, s[10:11]
	ds_write_b32 v12, v29 offset:5544
	s_cbranch_vccnz .LBB0_965
	s_ashr_i32 s47, s46, 31
	v_lshl_add_u64 v[40:41], s[46:47], 0, v[0:1]
	v_lshl_add_u64 v[40:41], v[40:41], 2, s[44:45]
	s_waitcnt vmcnt(9)
	v_mov_b32_e32 v29, v118
	v_mul_f32_e32 v29, v76, v29
	v_mul_f32_e32 v27, v27, v29
.LBB0_965:
	s_and_b64 vcc, exec, s[10:11]
	ds_write_b32 v12, v27 offset:5808
	s_cbranch_vccnz .LBB0_967
	s_ashr_i32 s47, s46, 31
	v_lshl_add_u64 v[40:41], s[46:47], 0, v[0:1]
	v_lshl_add_u64 v[40:41], v[40:41], 2, s[44:45]
	s_waitcnt vmcnt(8)
	v_mov_b32_e32 v27, v119
	v_mul_f32_e32 v27, v76, v27
	v_mul_f32_e32 v18, v18, v27
.LBB0_967:
	s_and_b64 vcc, exec, s[10:11]
	ds_write_b32 v12, v18 offset:6072
	s_cbranch_vccnz .LBB0_969
	s_ashr_i32 s47, s46, 31
	v_lshl_add_u64 v[40:41], s[46:47], 0, v[0:1]
	v_lshl_add_u64 v[40:41], v[40:41], 2, s[44:45]
	s_waitcnt vmcnt(7)
	v_mov_b32_e32 v18, v120
	v_mul_f32_e32 v18, v76, v18
	v_mul_f32_e32 v30, v30, v18
.LBB0_969:
	s_and_b64 vcc, exec, s[10:11]
	ds_write_b32 v12, v30 offset:6336
	s_cbranch_vccnz .LBB0_971
	s_ashr_i32 s47, s46, 31
	v_lshl_add_u64 v[30:31], s[46:47], 0, v[0:1]
	v_lshl_add_u64 v[30:31], v[30:31], 2, s[44:45]
	s_waitcnt vmcnt(6)
	v_mov_b32_e32 v18, v121
	v_mul_f32_e32 v18, v76, v18
	v_mul_f32_e32 v28, v28, v18
.LBB0_971:
	s_and_b64 vcc, exec, s[10:11]
	ds_write_b32 v12, v28 offset:6600
	s_cbranch_vccnz .LBB0_973
	s_ashr_i32 s47, s46, 31
	v_lshl_add_u64 v[28:29], s[46:47], 0, v[0:1]
	v_lshl_add_u64 v[28:29], v[28:29], 2, s[44:45]
	s_waitcnt vmcnt(5)
	v_mov_b32_e32 v18, v122
	v_mul_f32_e32 v18, v76, v18
	v_mul_f32_e32 v19, v19, v18
.LBB0_973:
	s_and_b64 vcc, exec, s[10:11]
	ds_write_b32 v12, v19 offset:6864
	s_cbranch_vccnz .LBB0_975
	s_ashr_i32 s47, s46, 31
	v_lshl_add_u64 v[18:19], s[46:47], 0, v[0:1]
	v_lshl_add_u64 v[18:19], v[18:19], 2, s[44:45]
	s_waitcnt vmcnt(4)
	v_mov_b32_e32 v18, v123
	v_mul_f32_e32 v18, v76, v18
	v_mul_f32_e32 v17, v17, v18
.LBB0_975:
	s_and_b64 vcc, exec, s[10:11]
	ds_write_b32 v12, v17 offset:7128
	s_cbranch_vccnz .LBB0_977
	s_ashr_i32 s47, s46, 31
	v_lshl_add_u64 v[18:19], s[46:47], 0, v[0:1]
	v_lshl_add_u64 v[18:19], v[18:19], 2, s[44:45]
	s_waitcnt vmcnt(3)
	v_mov_b32_e32 v17, v124
	v_mul_f32_e32 v17, v76, v17
	v_mul_f32_e32 v16, v16, v17
.LBB0_977:
	s_and_b64 vcc, exec, s[10:11]
	ds_write_b32 v12, v16 offset:7392
	s_cbranch_vccnz .LBB0_979
	s_ashr_i32 s47, s46, 31
	v_lshl_add_u64 v[16:17], s[46:47], 0, v[0:1]
	v_lshl_add_u64 v[16:17], v[16:17], 2, s[44:45]
	s_waitcnt vmcnt(2)
	v_mov_b32_e32 v16, v125
	v_mul_f32_e32 v16, v76, v16
	v_mul_f32_e32 v15, v15, v16
.LBB0_979:
	s_and_b64 vcc, exec, s[10:11]
	ds_write_b32 v12, v15 offset:7656
	s_cbranch_vccnz .LBB0_981
	s_ashr_i32 s47, s46, 31
	v_lshl_add_u64 v[16:17], s[46:47], 0, v[0:1]
	v_lshl_add_u64 v[16:17], v[16:17], 2, s[44:45]
	s_waitcnt vmcnt(1)
	v_mov_b32_e32 v15, v126
	v_mul_f32_e32 v15, v76, v15
	v_mul_f32_e32 v14, v14, v15
.LBB0_981:
	s_and_b64 vcc, exec, s[10:11]
	ds_write_b32 v12, v14 offset:7920
	s_cbranch_vccnz .LBB0_983
	s_ashr_i32 s47, s46, 31
	v_lshl_add_u64 v[14:15], s[46:47], 0, v[0:1]
	v_lshl_add_u64 v[14:15], v[14:15], 2, s[44:45]
	s_waitcnt vmcnt(0)
	v_mov_b32_e32 v14, v127
	v_mul_f32_e32 v14, v76, v14
	v_mul_f32_e32 v13, v13, v14

.LBB0_1352:
	s_lshl_b32 s56, s56, 1
	s_add_i32 s63, s26, s27
	v_add_u32_e32 v0, s56, v242
	s_add_i32 s56, s63, -5
	v_cvt_f32_i32_e32 v99, s56
	ds_read_b64_tr_b16 v[204:205], v0 offset:24576
	ds_read_b64_tr_b16 v[206:207], v0 offset:25088
	v_lshrrev_b32_e32 v99, 16, v99
	v_cndmask_b32_e64 v99, 0, v99, s[10:11]
	v_mov_b32_e32 v100, v240
	v_lshlrev_b32_e32 v101, 16, v99
	v_or_b32_e32 v142, v101, v99
	v_lshl_or_b32 v140, v100, 16, v100
	v_or_b32_e32 v141, v100, v101
	v_add_f32_e32 v99, v82, v83
	v_add_f32_e32 v99, v84, v99
	v_mfma_f32_32x32x16_bf16 v[116:131], v[140:143], v[136:139], 0
	v_add_f32_e32 v99, v85, v99
	v_add_f32_e32 v99, v86, v99
	v_add_f32_e32 v99, v87, v99
	v_cvt_pk_bf16_f32 v168, v82, v83
	v_cvt_pk_bf16_f32 v169, v84, v85
	s_waitcnt lgkmcnt(9)
	v_mfma_f32_32x32x16_bf16 v[116:131], v[200:203], v[160:163], v[116:131]
	ds_read_b64_tr_b16 v[82:83], v0 offset:28672
	ds_read_b64_tr_b16 v[84:85], v0 offset:29184
	v_mov_b32_e32 v100, v239
	v_add_f32_e32 v99, v88, v99
	v_lshl_or_b32 v140, v100, 16, v100
	v_or_b32_e32 v141, v100, v101
	v_add_f32_e32 v99, v89, v99
	v_add_f32_e32 v99, v90, v99
	v_mfma_f32_32x32x16_bf16 v[100:115], v[140:143], v[136:139], 0
	v_add_f32_e32 v99, v91, v99
	v_cvt_pk_bf16_f32 v170, v86, v87
	v_cvt_pk_bf16_f32 v171, v88, v89
	s_waitcnt lgkmcnt(10)
	v_mfma_f32_32x32x16_bf16 v[100:115], v[196:199], v[160:163], v[100:115]
	ds_read_b64_tr_b16 v[86:87], v0 offset:32768
	ds_read_b64_tr_b16 v[88:89], v0 offset:33280
	s_waitcnt lgkmcnt(11)
	v_mfma_f32_32x32x16_bf16 v[116:131], v[192:195], v[152:155], v[116:131]
	v_add_f32_e32 v99, v92, v99
	v_add_f32_e32 v99, v93, v99
	v_add_f32_e32 v99, v94, v99
	v_add_f32_e32 v99, v95, v99
	v_cvt_pk_bf16_f32 v164, v90, v91
	v_cvt_pk_bf16_f32 v165, v92, v93
	ds_read_b64_tr_b16 v[90:91], v0 offset:36864
	ds_read_b64_tr_b16 v[92:93], v0 offset:37376
	s_waitcnt lgkmcnt(12)
	v_mfma_f32_32x32x16_bf16 v[100:115], v[188:191], v[152:155], v[100:115]
	v_add_f32_e32 v99, v96, v99
	v_add_f32_e32 v99, v97, v99
	v_add_f32_e32 v99, v66, v99
	v_add_f32_e32 v99, v67, v99
	v_cvt_pk_bf16_f32 v166, v94, v95
	v_cvt_pk_bf16_f32 v167, v96, v97
	ds_read_b64_tr_b16 v[94:95], v0 offset:25600
	ds_read_b64_tr_b16 v[96:97], v0 offset:26112
	s_waitcnt lgkmcnt(13)
	v_mfma_f32_32x32x16_bf16 v[116:131], v[184:187], v[148:151], v[116:131]
	v_add_f32_e32 v99, v68, v99
	v_add_f32_e32 v99, v69, v99
	v_add_f32_e32 v99, v70, v99
	v_add_f32_e32 v99, v71, v99
	v_cvt_pk_bf16_f32 v156, v66, v67
	v_cvt_pk_bf16_f32 v157, v68, v69
	ds_read_b64_tr_b16 v[66:67], v0 offset:29696
	ds_read_b64_tr_b16 v[68:69], v0 offset:30208
	s_waitcnt lgkmcnt(14)
	v_mfma_f32_32x32x16_bf16 v[100:115], v[180:183], v[148:151], v[100:115]
	v_add_f32_e32 v99, v72, v99
	v_add_f32_e32 v99, v73, v99
	v_add_f32_e32 v99, v74, v99
	v_add_f32_e32 v99, v75, v99
	v_cvt_pk_bf16_f32 v158, v70, v71
	v_cvt_pk_bf16_f32 v159, v72, v73
	ds_read_b64_tr_b16 v[70:71], v0 offset:33792
	ds_read_b64_tr_b16 v[72:73], v0 offset:34304
	s_waitcnt lgkmcnt(14)
	v_mfma_f32_32x32x16_bf16 v[116:131], v[176:179], v[132:135], v[116:131]
	v_add_f32_e32 v99, v76, v99
	v_add_f32_e32 v99, v77, v99
	v_add_f32_e32 v99, v78, v99
	v_add_f32_e32 v99, v79, v99
	v_cvt_pk_bf16_f32 v144, v74, v75
	v_cvt_pk_bf16_f32 v145, v76, v77
	ds_read_b64_tr_b16 v[74:75], v0 offset:37888
	ds_read_b64_tr_b16 v[76:77], v0 offset:38400
	v_mfma_f32_32x32x16_bf16 v[100:115], v[172:175], v[132:135], v[100:115]
	v_add_f32_e32 v99, v80, v99
	v_add_f32_e32 v99, v81, v99
	v_add_f32_e32 v99, 0, v99
	v_cvt_pk_bf16_f32 v146, v78, v79
	v_cvt_pk_bf16_f32 v147, v80, v81
	v_lshl_add_u64 v[208:209], v[216:217], 0, s[54:55]
	v_lshl_add_u64 v[78:79], v[208:209], 0, s[46:47]
	s_add_i32 s56, s62, s91
	v_lshl_add_u64 v[210:211], v[218:219], 0, s[54:55]
	s_mov_b32 s57, m0
	s_mov_b32 m0, s56
	s_nop 0
	global_load_lds_dwordx4 v[78:79], off
	s_mov_b32 m0, s57
	v_lshl_add_u64 v[78:79], v[210:211], 0, s[40:41]
	s_lshl_b32 s56, s61, 1
	v_lshl_add_u64 v[222:223], v[220:221], 0, s[54:55]
	s_add_i32 s57, s56, s92
	s_mov_b32 s58, m0
	s_mov_b32 m0, s57
	s_nop 0
	global_load_lds_dwordx4 v[78:79], off
	s_mov_b32 m0, s58
	v_lshl_add_u64 v[78:79], v[222:223], 0, s[40:41]
	s_add_i32 s56, s56, s93
	s_mov_b32 s57, m0
	s_mov_b32 m0, s56
	s_nop 0
	global_load_lds_dwordx4 v[78:79], off
	s_mov_b32 m0, s57
	s_waitcnt lgkmcnt(14)
	v_mfma_f32_32x32x16_bf16 v[50:65], v[168:171], v[204:207], v[50:65]
	ds_read_b64_tr_b16 v[78:79], v0 offset:26624
	ds_read_b64_tr_b16 v[80:81], v0 offset:27136
	v_max_f32_e32 v253, v117, v117
	v_max_f32_e32 v254, v116, v116
	v_max_f32_e32 v253, v254, v253
	v_max3_f32 v254, v118, v119, v101
	v_max3_f32 v253, v253, v100, v102
	s_waitcnt lgkmcnt(14)
	v_mfma_f32_32x32x16_bf16 v[34:49], v[168:171], v[82:85], v[34:49]
	ds_read_b64_tr_b16 v[82:83], v0 offset:30720
	ds_read_b64_tr_b16 v[84:85], v0 offset:31232
	v_max3_f32 v253, v253, v103, v120
	v_max3_f32 v254, v254, v122, v123
	v_max3_f32 v253, v253, v121, v104
	v_max3_f32 v254, v254, v106, v107
	v_max3_f32 v253, v253, v105, v124
	s_waitcnt lgkmcnt(14)
	v_mfma_f32_32x32x16_bf16 v[18:33], v[168:171], v[86:89], v[18:33]
	ds_read_b64_tr_b16 v[86:87], v0 offset:34816
	ds_read_b64_tr_b16 v[88:89], v0 offset:35328
	v_max3_f32 v254, v254, v126, v127
	v_max3_f32 v253, v253, v125, v108
	v_max3_f32 v254, v254, v110, v111
	v_max3_f32 v253, v253, v109, v128
	v_max3_f32 v254, v254, v130, v131
	s_waitcnt lgkmcnt(14)
	v_mfma_f32_32x32x16_bf16 v[2:17], v[168:171], v[90:93], v[2:17]
	ds_read_b64_tr_b16 v[90:91], v0 offset:38912
	ds_read_b64_tr_b16 v[92:93], v0 offset:39424
	v_max3_f32 v253, v253, v129, v112
	v_max3_f32 v254, v254, v114, v115
	v_max3_f32 v253, v253, v113, v254
	v_mov_b32_e32 v254, v253
	s_nop 1
	v_permlane32_swap_b32_e32 v253, v254
	v_max_f32_e32 v254, v254, v254
	v_max_f32_e32 v253, v253, v253
	v_max_f32_e32 v253, v253, v254
	v_cmp_lt_f32_e32 vcc, s87, v253
	s_cmp_lg_u64 vcc, 0
	v_add_f32_e32 v98, v98, v99
	s_cselect_b64 s[56:57], -1, 0
	s_cbranch_vccnz .LBB0_1360
.LBB0_1353:
	s_waitcnt lgkmcnt(14)
	v_mfma_f32_32x32x16_bf16 v[50:65], v[164:167], v[94:97], v[50:65]
	v_exp_f32_e32 v124, v124
	v_exp_f32_e32 v125, v125
	v_exp_f32_e32 v116, v116
	ds_read_b64_tr_b16 v[94:95], v0 offset:27648
	ds_read_b64_tr_b16 v[96:97], v0 offset:28160
	s_waitcnt lgkmcnt(14)
	v_mfma_f32_32x32x16_bf16 v[34:49], v[164:167], v[66:69], v[34:49]
	v_exp_f32_e32 v126, v126
	v_exp_f32_e32 v127, v127
	v_exp_f32_e32 v117, v117
	ds_read_b64_tr_b16 v[200:201], v0 offset:31744
	ds_read_b64_tr_b16 v[202:203], v0 offset:32256
	s_waitcnt lgkmcnt(14)
	v_mfma_f32_32x32x16_bf16 v[18:33], v[164:167], v[70:73], v[18:33]
	v_exp_f32_e32 v128, v128
	v_exp_f32_e32 v129, v129
	v_exp_f32_e32 v118, v118
	ds_read_b64_tr_b16 v[70:71], v0 offset:35840
	ds_read_b64_tr_b16 v[72:73], v0 offset:36352
	s_waitcnt lgkmcnt(14)
	v_mfma_f32_32x32x16_bf16 v[2:17], v[164:167], v[74:77], v[2:17]
	v_exp_f32_e32 v130, v130
	v_exp_f32_e32 v131, v131
	v_exp_f32_e32 v119, v119
	ds_read_b64_tr_b16 v[74:75], v0 offset:39936
	ds_read_b64_tr_b16 v[76:77], v0 offset:40448
	v_add_u32_e32 v0, s61, v241
	ds_read_b128 v[66:69], v0
	ds_read_b128 v[196:199], v0 offset:512
	s_waitcnt lgkmcnt(14)
	v_mfma_f32_32x32x16_bf16 v[50:65], v[156:159], v[78:81], v[50:65]
	v_exp_f32_e32 v100, v100
	v_exp_f32_e32 v101, v101
	v_exp_f32_e32 v120, v120
	ds_read_b128 v[192:195], v0 offset:2048
	ds_read_b128 v[188:191], v0 offset:2560
	v_mfma_f32_32x32x16_bf16 v[34:49], v[156:159], v[82:85], v[34:49]
	v_exp_f32_e32 v102, v102
	v_exp_f32_e32 v103, v103
	v_exp_f32_e32 v121, v121
	ds_read_b128 v[184:187], v0 offset:4096
	ds_read_b128 v[180:183], v0 offset:4608
	s_waitcnt lgkmcnt(14)
	v_mfma_f32_32x32x16_bf16 v[18:33], v[156:159], v[86:89], v[18:33]
	v_exp_f32_e32 v104, v104
	v_exp_f32_e32 v105, v105
	v_exp_f32_e32 v122, v122
	ds_read_b128 v[176:179], v0 offset:6144
	ds_read_b128 v[172:175], v0 offset:6656
	v_mfma_f32_32x32x16_bf16 v[2:17], v[156:159], v[90:93], v[2:17]
	v_exp_f32_e32 v106, v106
	v_exp_f32_e32 v107, v107
	v_exp_f32_e32 v123, v123
	s_waitcnt lgkmcnt(14)
	v_mfma_f32_32x32x16_bf16 v[50:65], v[144:147], v[94:97], v[50:65]
	v_exp_f32_e32 v108, v108
	v_exp_f32_e32 v109, v109
	s_waitcnt lgkmcnt(12)
	v_mfma_f32_32x32x16_bf16 v[34:49], v[144:147], v[200:203], v[34:49]
	v_exp_f32_e32 v110, v110
	v_exp_f32_e32 v111, v111
	s_waitcnt lgkmcnt(10)
	v_mfma_f32_32x32x16_bf16 v[18:33], v[144:147], v[70:73], v[18:33]
	v_exp_f32_e32 v112, v112
	v_exp_f32_e32 v113, v113
	s_waitcnt lgkmcnt(8)
	v_mfma_f32_32x32x16_bf16 v[2:17], v[144:147], v[74:77], v[2:17]
	v_exp_f32_e32 v114, v114
	v_exp_f32_e32 v115, v115
	s_waitcnt vmcnt(3) lgkmcnt(0)
	s_barrier
	s_andn2_b64 vcc, exec, s[56:57]
	v_add_u32_e32 v0, s90, v244
	s_cbranch_vccnz .LBB0_1355
	s_waitcnt lgkmcnt(0)
	ds_read_b128 v[70:73], v0 offset:96
	ds_read_b128 v[74:77], v0 offset:64
	ds_read_b128 v[78:81], v0 offset:32
	ds_read_b128 v[82:85], v0
	s_waitcnt lgkmcnt(3)
	v_pk_mul_f32 v[62:63], v[62:63], v[70:71]
	s_waitcnt lgkmcnt(2)
	v_pk_mul_f32 v[58:59], v[58:59], v[74:75]
	s_waitcnt lgkmcnt(1)
	v_pk_mul_f32 v[54:55], v[54:55], v[78:79]
	v_pk_mul_f32 v[64:65], v[64:65], v[72:73]
	v_pk_mul_f32 v[60:61], v[60:61], v[76:77]
	v_pk_mul_f32 v[56:57], v[56:57], v[80:81]
	s_waitcnt lgkmcnt(0)
	v_pk_mul_f32 v[52:53], v[52:53], v[84:85]
	v_pk_mul_f32 v[50:51], v[50:51], v[82:83]
	v_pk_mul_f32 v[46:47], v[46:47], v[70:71]
	v_pk_mul_f32 v[42:43], v[42:43], v[74:75]
	v_pk_mul_f32 v[38:39], v[38:39], v[78:79]
	v_pk_mul_f32 v[48:49], v[48:49], v[72:73]
	v_pk_mul_f32 v[44:45], v[44:45], v[76:77]
	v_pk_mul_f32 v[40:41], v[40:41], v[80:81]
	v_pk_mul_f32 v[36:37], v[36:37], v[84:85]
	v_pk_mul_f32 v[34:35], v[34:35], v[82:83]
	v_pk_mul_f32 v[30:31], v[30:31], v[70:71]
	v_pk_mul_f32 v[26:27], v[26:27], v[74:75]
	v_pk_mul_f32 v[22:23], v[22:23], v[78:79]
	v_pk_mul_f32 v[32:33], v[32:33], v[72:73]
	v_pk_mul_f32 v[28:29], v[28:29], v[76:77]
	v_pk_mul_f32 v[24:25], v[24:25], v[80:81]
	v_pk_mul_f32 v[20:21], v[20:21], v[84:85]
	v_pk_mul_f32 v[18:19], v[18:19], v[82:83]
	v_pk_mul_f32 v[14:15], v[14:15], v[70:71]
	v_pk_mul_f32 v[10:11], v[10:11], v[74:75]
	v_pk_mul_f32 v[6:7], v[6:7], v[78:79]
	v_pk_mul_f32 v[16:17], v[16:17], v[72:73]
	v_pk_mul_f32 v[12:13], v[12:13], v[76:77]
	v_pk_mul_f32 v[8:9], v[8:9], v[80:81]
	v_pk_mul_f32 v[4:5], v[4:5], v[84:85]
	v_pk_mul_f32 v[2:3], v[2:3], v[82:83]
.LBB0_1355:
	s_add_i32 s56, s61, 0x2000
	s_cmpk_lg_i32 s61, 0x4000
	s_cselect_b32 s95, s56, 0
	s_lshl_b32 s56, s62, 1
	s_add_i32 s63, s63, -4
	v_add_u32_e32 v99, s56, v242
	v_cvt_f32_i32_e32 v70, s63
	ds_read_b64_tr_b16 v[200:201], v99 offset:24576
	ds_read_b64_tr_b16 v[202:203], v99 offset:25088
	v_lshrrev_b32_e32 v70, 16, v70
	v_cndmask_b32_e64 v70, 0, v70, s[10:11]
	v_mov_b32_e32 v71, v240
	v_lshlrev_b32_e32 v72, 16, v70
	v_or_b32_e32 v142, v72, v70
	v_lshl_or_b32 v140, v71, 16, v71
	v_or_b32_e32 v141, v71, v72
	v_add_f32_e32 v70, v116, v117
	v_cvt_pk_bf16_f32 v168, v116, v117
	v_mfma_f32_32x32x16_bf16 v[82:97], v[140:143], v[136:139], 0
	v_cvt_pk_bf16_f32 v169, v118, v119
	s_waitcnt lgkmcnt(9)
	v_mfma_f32_32x32x16_bf16 v[82:97], v[66:69], v[160:163], v[82:97]
	v_add_f32_e32 v66, v118, v70
	v_add_f32_e32 v66, v119, v66
	v_add_f32_e32 v66, v120, v66
	v_add_f32_e32 v144, v121, v66
	ds_read_b64_tr_b16 v[116:117], v99 offset:28672
	ds_read_b64_tr_b16 v[118:119], v99 offset:29184
	v_mov_b32_e32 v66, v239
	v_cvt_pk_bf16_f32 v170, v120, v121
	v_lshl_or_b32 v140, v66, 16, v66
	v_or_b32_e32 v141, v66, v72
	v_cvt_pk_bf16_f32 v171, v122, v123
	s_nop 0
	v_mfma_f32_32x32x16_bf16 v[66:81], v[140:143], v[136:139], 0
	v_add_f32_e32 v140, v122, v144
	v_add_f32_e32 v140, v123, v140
	v_add_f32_e32 v140, v124, v140
	v_add_f32_e32 v140, v125, v140
	s_waitcnt lgkmcnt(10)
	v_mfma_f32_32x32x16_bf16 v[66:81], v[196:199], v[160:163], v[66:81]
	ds_read_b64_tr_b16 v[120:121], v99 offset:32768
	ds_read_b64_tr_b16 v[122:123], v99 offset:33280
	s_waitcnt lgkmcnt(11)
	v_mfma_f32_32x32x16_bf16 v[82:97], v[192:195], v[152:155], v[82:97]
	v_add_f32_e32 v140, v126, v140
	v_add_f32_e32 v140, v127, v140
	v_add_f32_e32 v140, v128, v140
	v_add_f32_e32 v140, v129, v140
	v_cvt_pk_bf16_f32 v164, v124, v125
	v_cvt_pk_bf16_f32 v165, v126, v127
	ds_read_b64_tr_b16 v[124:125], v99 offset:36864
	ds_read_b64_tr_b16 v[126:127], v99 offset:37376
	s_waitcnt lgkmcnt(12)
	v_mfma_f32_32x32x16_bf16 v[66:81], v[188:191], v[152:155], v[66:81]
	v_add_f32_e32 v140, v130, v140
	v_add_f32_e32 v140, v131, v140
	v_add_f32_e32 v140, v100, v140
	v_add_f32_e32 v140, v101, v140
	v_cvt_pk_bf16_f32 v166, v128, v129
	v_cvt_pk_bf16_f32 v167, v130, v131
	ds_read_b64_tr_b16 v[128:129], v99 offset:25600
	ds_read_b64_tr_b16 v[130:131], v99 offset:26112
	s_waitcnt lgkmcnt(13)
	v_mfma_f32_32x32x16_bf16 v[82:97], v[184:187], v[148:151], v[82:97]
	v_add_f32_e32 v140, v102, v140
	v_add_f32_e32 v140, v103, v140
	v_add_f32_e32 v140, v104, v140
	v_add_f32_e32 v140, v105, v140
	v_cvt_pk_bf16_f32 v156, v100, v101
	v_cvt_pk_bf16_f32 v157, v102, v103
	ds_read_b64_tr_b16 v[100:101], v99 offset:29696
	ds_read_b64_tr_b16 v[102:103], v99 offset:30208
	s_waitcnt lgkmcnt(14)
	v_mfma_f32_32x32x16_bf16 v[66:81], v[180:183], v[148:151], v[66:81]
	v_add_f32_e32 v140, v106, v140
	v_add_f32_e32 v140, v107, v140
	v_add_f32_e32 v140, v108, v140
	v_add_f32_e32 v140, v109, v140
	v_cvt_pk_bf16_f32 v158, v104, v105
	v_cvt_pk_bf16_f32 v159, v106, v107
	ds_read_b64_tr_b16 v[104:105], v99 offset:33792
	ds_read_b64_tr_b16 v[106:107], v99 offset:34304
	s_waitcnt lgkmcnt(14)
	v_mfma_f32_32x32x16_bf16 v[82:97], v[176:179], v[132:135], v[82:97]
	v_add_f32_e32 v140, v110, v140
	v_add_f32_e32 v140, v111, v140
	v_add_f32_e32 v140, v112, v140
	v_add_f32_e32 v140, v113, v140
	v_cvt_pk_bf16_f32 v144, v108, v109
	v_cvt_pk_bf16_f32 v145, v110, v111
	ds_read_b64_tr_b16 v[108:109], v99 offset:37888
	ds_read_b64_tr_b16 v[110:111], v99 offset:38400
	v_mfma_f32_32x32x16_bf16 v[66:81], v[172:175], v[132:135], v[66:81]
	v_add_f32_e32 v140, v114, v140
	v_add_f32_e32 v140, v115, v140
	v_add_f32_e32 v140, 0, v140
	v_cvt_pk_bf16_f32 v146, v112, v113
	v_cvt_pk_bf16_f32 v147, v114, v115
	v_lshl_add_u64 v[112:113], v[208:209], 0, s[48:49]
	s_add_i32 s56, s61, s91
	s_mov_b32 s57, m0
	s_mov_b32 m0, s56
	s_nop 0
	global_load_lds_dwordx4 v[112:113], off
	s_mov_b32 m0, s57
	v_lshl_add_u64 v[112:113], v[210:211], 0, s[42:43]
	s_lshl_b32 s56, s95, 1
	s_add_i32 s57, s56, s92
	s_mov_b32 s58, m0
	s_mov_b32 m0, s57
	s_nop 0
	global_load_lds_dwordx4 v[112:113], off
	s_mov_b32 m0, s58
	v_lshl_add_u64 v[112:113], v[222:223], 0, s[42:43]
	s_add_i32 s56, s56, s93
	s_mov_b32 s57, m0
	s_mov_b32 m0, s56
	s_nop 0
	global_load_lds_dwordx4 v[112:113], off
	s_mov_b32 m0, s57
	s_waitcnt lgkmcnt(14)
	v_mfma_f32_32x32x16_bf16 v[50:65], v[168:171], v[200:203], v[50:65]
	ds_read_b64_tr_b16 v[112:113], v99 offset:26624
	ds_read_b64_tr_b16 v[114:115], v99 offset:27136
	v_max_f32_e32 v253, v83, v83
	v_max_f32_e32 v254, v82, v82
	v_max_f32_e32 v253, v254, v253
	v_max3_f32 v254, v84, v85, v67
	v_max3_f32 v253, v253, v66, v68
	s_waitcnt lgkmcnt(14)
	v_mfma_f32_32x32x16_bf16 v[34:49], v[168:171], v[116:119], v[34:49]
	ds_read_b64_tr_b16 v[116:117], v99 offset:30720
	ds_read_b64_tr_b16 v[118:119], v99 offset:31232
	v_max3_f32 v253, v253, v69, v86
	v_max3_f32 v254, v254, v88, v89
	v_max3_f32 v253, v253, v87, v70
	v_max3_f32 v254, v254, v72, v73
	v_max3_f32 v253, v253, v71, v90
	s_waitcnt lgkmcnt(14)
	v_mfma_f32_32x32x16_bf16 v[18:33], v[168:171], v[120:123], v[18:33]
	ds_read_b64_tr_b16 v[120:121], v99 offset:34816
	ds_read_b64_tr_b16 v[122:123], v99 offset:35328
	v_max3_f32 v254, v254, v92, v93
	v_max3_f32 v253, v253, v91, v74
	v_max3_f32 v254, v254, v76, v77
	v_max3_f32 v253, v253, v75, v94
	v_max3_f32 v254, v254, v96, v97
	s_waitcnt lgkmcnt(14)
	v_mfma_f32_32x32x16_bf16 v[2:17], v[168:171], v[124:127], v[2:17]
	ds_read_b64_tr_b16 v[124:125], v99 offset:38912
	ds_read_b64_tr_b16 v[126:127], v99 offset:39424
	v_max3_f32 v253, v253, v95, v78
	v_max3_f32 v254, v254, v80, v81
	v_max3_f32 v253, v253, v79, v254
	v_mov_b32_e32 v254, v253
	s_nop 1
	v_permlane32_swap_b32_e32 v253, v254
	v_max_f32_e32 v254, v254, v254
	v_max_f32_e32 v253, v253, v253
	v_max_f32_e32 v253, v253, v254
	v_cmp_lt_f32_e32 vcc, s87, v253
	s_cmp_lg_u64 vcc, 0
	v_add_f32_e32 v98, v98, v140
	s_cselect_b64 s[56:57], -1, 0
	s_cbranch_vccnz .LBB0_1363
.LBB0_1356:
	s_waitcnt lgkmcnt(14)
	v_mfma_f32_32x32x16_bf16 v[50:65], v[164:167], v[128:131], v[50:65]
	v_exp_f32_e32 v90, v90
	v_exp_f32_e32 v91, v91
	v_exp_f32_e32 v82, v82
	ds_read_b64_tr_b16 v[128:129], v99 offset:27648
	ds_read_b64_tr_b16 v[130:131], v99 offset:28160
	s_waitcnt lgkmcnt(14)
	v_mfma_f32_32x32x16_bf16 v[34:49], v[164:167], v[100:103], v[34:49]
	v_exp_f32_e32 v92, v92
	v_exp_f32_e32 v93, v93
	v_exp_f32_e32 v83, v83
	ds_read_b64_tr_b16 v[100:101], v99 offset:31744
	ds_read_b64_tr_b16 v[102:103], v99 offset:32256
	s_waitcnt lgkmcnt(14)
	v_mfma_f32_32x32x16_bf16 v[18:33], v[164:167], v[104:107], v[18:33]
	v_exp_f32_e32 v94, v94
	v_exp_f32_e32 v95, v95
	v_exp_f32_e32 v84, v84
	ds_read_b64_tr_b16 v[104:105], v99 offset:35840
	ds_read_b64_tr_b16 v[106:107], v99 offset:36352
	s_waitcnt lgkmcnt(14)
	v_mfma_f32_32x32x16_bf16 v[2:17], v[164:167], v[108:111], v[2:17]
	v_exp_f32_e32 v96, v96
	v_exp_f32_e32 v97, v97
	v_exp_f32_e32 v85, v85
	ds_read_b64_tr_b16 v[108:109], v99 offset:39936
	ds_read_b64_tr_b16 v[110:111], v99 offset:40448
	v_add_u32_e32 v99, s95, v241
	ds_read_b128 v[200:203], v99
	ds_read_b128 v[196:199], v99 offset:512
	s_waitcnt lgkmcnt(14)
	v_mfma_f32_32x32x16_bf16 v[50:65], v[156:159], v[112:115], v[50:65]
	v_exp_f32_e32 v66, v66
	v_exp_f32_e32 v67, v67
	v_exp_f32_e32 v86, v86
	ds_read_b128 v[192:195], v99 offset:2048
	ds_read_b128 v[188:191], v99 offset:2560
	v_mfma_f32_32x32x16_bf16 v[34:49], v[156:159], v[116:119], v[34:49]
	v_exp_f32_e32 v68, v68
	v_exp_f32_e32 v69, v69
	v_exp_f32_e32 v87, v87
	ds_read_b128 v[184:187], v99 offset:4096
	ds_read_b128 v[180:183], v99 offset:4608
	s_waitcnt lgkmcnt(14)
	v_mfma_f32_32x32x16_bf16 v[18:33], v[156:159], v[120:123], v[18:33]
	v_exp_f32_e32 v70, v70
	v_exp_f32_e32 v71, v71
	v_exp_f32_e32 v88, v88
	ds_read_b128 v[176:179], v99 offset:6144
	ds_read_b128 v[172:175], v99 offset:6656
	v_mfma_f32_32x32x16_bf16 v[2:17], v[156:159], v[124:127], v[2:17]
	v_exp_f32_e32 v72, v72
	v_exp_f32_e32 v73, v73
	v_exp_f32_e32 v89, v89
	s_waitcnt lgkmcnt(14)
	v_mfma_f32_32x32x16_bf16 v[50:65], v[144:147], v[128:131], v[50:65]
	v_exp_f32_e32 v74, v74
	v_exp_f32_e32 v75, v75
	s_waitcnt lgkmcnt(12)
	v_mfma_f32_32x32x16_bf16 v[34:49], v[144:147], v[100:103], v[34:49]
	v_exp_f32_e32 v76, v76
	v_exp_f32_e32 v77, v77
	s_waitcnt lgkmcnt(10)
	v_mfma_f32_32x32x16_bf16 v[18:33], v[144:147], v[104:107], v[18:33]
	v_exp_f32_e32 v78, v78
	v_exp_f32_e32 v79, v79
	s_waitcnt lgkmcnt(8)
	v_mfma_f32_32x32x16_bf16 v[2:17], v[144:147], v[108:111], v[2:17]
	v_exp_f32_e32 v80, v80
	v_exp_f32_e32 v81, v81
	s_waitcnt vmcnt(3) lgkmcnt(0)
	s_barrier
	s_andn2_b64 vcc, exec, s[56:57]
	s_cbranch_vccnz .LBB0_1358
	s_waitcnt lgkmcnt(0)
	ds_read_b128 v[100:103], v0 offset:96
	ds_read_b128 v[104:107], v0 offset:64
	ds_read_b128 v[108:111], v0 offset:32
	ds_read_b128 v[112:115], v0
	s_waitcnt lgkmcnt(3)
	v_pk_mul_f32 v[62:63], v[62:63], v[100:101]
	s_waitcnt lgkmcnt(2)
	v_pk_mul_f32 v[58:59], v[58:59], v[104:105]
	s_waitcnt lgkmcnt(1)
	v_pk_mul_f32 v[54:55], v[54:55], v[108:109]
	v_pk_mul_f32 v[64:65], v[64:65], v[102:103]
	v_pk_mul_f32 v[60:61], v[60:61], v[106:107]
	v_pk_mul_f32 v[56:57], v[56:57], v[110:111]
	s_waitcnt lgkmcnt(0)
	v_pk_mul_f32 v[52:53], v[52:53], v[114:115]
	v_pk_mul_f32 v[50:51], v[50:51], v[112:113]
	v_pk_mul_f32 v[46:47], v[46:47], v[100:101]
	v_pk_mul_f32 v[42:43], v[42:43], v[104:105]
	v_pk_mul_f32 v[38:39], v[38:39], v[108:109]
	v_pk_mul_f32 v[48:49], v[48:49], v[102:103]
	v_pk_mul_f32 v[44:45], v[44:45], v[106:107]
	v_pk_mul_f32 v[40:41], v[40:41], v[110:111]
	v_pk_mul_f32 v[36:37], v[36:37], v[114:115]
	v_pk_mul_f32 v[34:35], v[34:35], v[112:113]
	v_pk_mul_f32 v[30:31], v[30:31], v[100:101]
	v_pk_mul_f32 v[26:27], v[26:27], v[104:105]
	v_pk_mul_f32 v[22:23], v[22:23], v[108:109]
	v_pk_mul_f32 v[32:33], v[32:33], v[102:103]
	v_pk_mul_f32 v[28:29], v[28:29], v[106:107]
	v_pk_mul_f32 v[24:25], v[24:25], v[110:111]
	v_pk_mul_f32 v[20:21], v[20:21], v[114:115]
	v_pk_mul_f32 v[18:19], v[18:19], v[112:113]
	v_pk_mul_f32 v[14:15], v[14:15], v[100:101]
	v_pk_mul_f32 v[10:11], v[10:11], v[104:105]
	v_pk_mul_f32 v[6:7], v[6:7], v[108:109]
	v_pk_mul_f32 v[16:17], v[16:17], v[102:103]
	v_pk_mul_f32 v[12:13], v[12:13], v[106:107]
	v_pk_mul_f32 v[8:9], v[8:9], v[110:111]
	v_pk_mul_f32 v[4:5], v[4:5], v[114:115]
	v_pk_mul_f32 v[2:3], v[2:3], v[112:113]

.LBB0_1360:
	v_max_f32_e32 v253, v253, v253
	v_max_f32_e32 v253, 0, v253
	v_ceil_f32_e32 v254, v253
	v_exp_f32_e64 v253, -v254
	s_and_saveexec_b64 s[58:59], s[10:11]
	ds_write_b32 v237, v253
	s_or_b64 exec, exec, s[58:59]
	v_add_f32_e32 v243, v243, v254
	v_sub_f32_e32 v131, v131, v254
	v_sub_f32_e32 v130, v130, v254
	v_sub_f32_e32 v129, v129, v254
	v_sub_f32_e32 v128, v128, v254
	v_sub_f32_e32 v127, v127, v254
	v_sub_f32_e32 v126, v126, v254
	v_sub_f32_e32 v125, v125, v254
	v_sub_f32_e32 v124, v124, v254
	v_sub_f32_e32 v123, v123, v254
	v_sub_f32_e32 v122, v122, v254
	v_sub_f32_e32 v121, v121, v254
	v_sub_f32_e32 v120, v120, v254
	v_sub_f32_e32 v119, v119, v254
	v_sub_f32_e32 v118, v118, v254
	v_sub_f32_e32 v117, v117, v254
	v_sub_f32_e32 v116, v116, v254
	v_sub_f32_e32 v115, v115, v254
	v_sub_f32_e32 v114, v114, v254
	v_sub_f32_e32 v113, v113, v254
	v_sub_f32_e32 v112, v112, v254
	v_sub_f32_e32 v111, v111, v254
	v_sub_f32_e32 v110, v110, v254
	v_sub_f32_e32 v109, v109, v254
	v_sub_f32_e32 v108, v108, v254
	v_sub_f32_e32 v107, v107, v254
	v_sub_f32_e32 v106, v106, v254
	v_sub_f32_e32 v105, v105, v254
	v_sub_f32_e32 v104, v104, v254
	v_sub_f32_e32 v103, v103, v254
	v_sub_f32_e32 v102, v102, v254
	v_sub_f32_e32 v101, v101, v254
	v_sub_f32_e32 v100, v100, v254
	v_bfe_u32 v254, v243, 16, 1
	v_add3_u32 v254, v243, v254, s85
	v_and_b32_e32 v254, 0xffff0000, v254
	v_sub_f32_e32 v255, v243, v254
	v_xor_b32_e32 v254, 0x80000000, v254
	v_lshrrev_b32_e32 v254, 16, v254
	v_xor_b32_e32 v255, 0x80000000, v255
	v_and_or_b32 v254, v255, s86, v254
	v_cndmask_b32_e64 v139, 0, v254, s[10:11]
	v_mul_f32_e32 v98, v98, v253
	s_branch .LBB0_1353
.LBB0_1363:
	v_max_f32_e32 v253, v253, v253
	v_max_f32_e32 v253, 0, v253
	v_ceil_f32_e32 v254, v253
	v_exp_f32_e64 v253, -v254
	s_and_saveexec_b64 s[58:59], s[10:11]
	ds_write_b32 v237, v253
	s_or_b64 exec, exec, s[58:59]
	v_add_f32_e32 v243, v243, v254
	v_sub_f32_e32 v97, v97, v254
	v_sub_f32_e32 v96, v96, v254
	v_sub_f32_e32 v95, v95, v254
	v_sub_f32_e32 v94, v94, v254
	v_sub_f32_e32 v93, v93, v254
	v_sub_f32_e32 v92, v92, v254
	v_sub_f32_e32 v91, v91, v254
	v_sub_f32_e32 v90, v90, v254
	v_sub_f32_e32 v89, v89, v254
	v_sub_f32_e32 v88, v88, v254
	v_sub_f32_e32 v87, v87, v254
	v_sub_f32_e32 v86, v86, v254
	v_sub_f32_e32 v85, v85, v254
	v_sub_f32_e32 v84, v84, v254
	v_sub_f32_e32 v83, v83, v254
	v_sub_f32_e32 v82, v82, v254
	v_sub_f32_e32 v81, v81, v254
	v_sub_f32_e32 v80, v80, v254
	v_sub_f32_e32 v79, v79, v254
	v_sub_f32_e32 v78, v78, v254
	v_sub_f32_e32 v77, v77, v254
	v_sub_f32_e32 v76, v76, v254
	v_sub_f32_e32 v75, v75, v254
	v_sub_f32_e32 v74, v74, v254
	v_sub_f32_e32 v73, v73, v254
	v_sub_f32_e32 v72, v72, v254
	v_sub_f32_e32 v71, v71, v254
	v_sub_f32_e32 v70, v70, v254
	v_sub_f32_e32 v69, v69, v254
	v_sub_f32_e32 v68, v68, v254
	v_sub_f32_e32 v67, v67, v254
	v_sub_f32_e32 v66, v66, v254
	v_bfe_u32 v254, v243, 16, 1
	v_add3_u32 v254, v243, v254, s85
	v_and_b32_e32 v254, 0xffff0000, v254
	v_sub_f32_e32 v255, v243, v254
	v_xor_b32_e32 v254, 0x80000000, v254
	v_lshrrev_b32_e32 v254, 16, v254
	v_xor_b32_e32 v255, 0x80000000, v255
	v_and_or_b32 v254, v255, s86, v254
	v_cndmask_b32_e64 v139, 0, v254, s[10:11]
	v_mul_f32_e32 v98, v98, v253
	s_branch .LBB0_1356

	.amdhsa_kernel _Z14fwd_megakernel6Params
		.amdhsa_group_segment_fixed_size 0
		.amdhsa_private_segment_fixed_size 0
		.amdhsa_kernarg_size 424
		.amdhsa_user_sgpr_count 2
		.amdhsa_user_sgpr_dispatch_ptr 0
		.amdhsa_user_sgpr_queue_ptr 0
		.amdhsa_user_sgpr_kernarg_segment_ptr 1
		.amdhsa_user_sgpr_dispatch_id 0
		.amdhsa_user_sgpr_kernarg_preload_length 0
		.amdhsa_user_sgpr_kernarg_preload_offset 0
		.amdhsa_user_sgpr_private_segment_size 0
		.amdhsa_uses_dynamic_stack 0
		.amdhsa_enable_private_segment 0
		.amdhsa_system_sgpr_workgroup_id_x 1
		.amdhsa_system_sgpr_workgroup_id_y 0
		.amdhsa_system_sgpr_workgroup_id_z 0
		.amdhsa_system_sgpr_workgroup_info 0
		.amdhsa_system_vgpr_workitem_id 2
		.amdhsa_next_free_vgpr 256
		.amdhsa_next_free_sgpr 98
		.amdhsa_accum_offset 256
		.amdhsa_reserve_vcc 1
		.amdhsa_float_round_mode_32 0
		.amdhsa_float_round_mode_16_64 0
		.amdhsa_float_denorm_mode_32 3
		.amdhsa_float_denorm_mode_16_64 3
		.amdhsa_dx10_clamp 1
		.amdhsa_ieee_mode 1
		.amdhsa_fp16_overflow 0
		.amdhsa_tg_split 0
		.amdhsa_exception_fp_ieee_invalid_op 0
		.amdhsa_exception_fp_denorm_src 0
		.amdhsa_exception_fp_ieee_div_zero 0
		.amdhsa_exception_fp_ieee_overflow 0
		.amdhsa_exception_fp_ieee_underflow 0
		.amdhsa_exception_fp_ieee_inexact 0
		.amdhsa_exception_int_div_zero 0
	.end_amdhsa_kernel

amdhsa.kernels:
  - .agpr_count:     0
    .args:
      - .offset:         0
        .size:           168
        .value_kind:     by_value
      - .offset:         168
        .size:           4
        .value_kind:     hidden_block_count_x
      - .offset:         172
        .size:           4
        .value_kind:     hidden_block_count_y
      - .offset:         176
        .size:           4
        .value_kind:     hidden_block_count_z
      - .offset:         180
        .size:           2
        .value_kind:     hidden_group_size_x
      - .offset:         182
        .size:           2
        .value_kind:     hidden_group_size_y
      - .offset:         184
        .size:           2
        .value_kind:     hidden_group_size_z
      - .offset:         186
        .size:           2
        .value_kind:     hidden_remainder_x
      - .offset:         188
        .size:           2
        .value_kind:     hidden_remainder_y
      - .offset:         190
        .size:           2
        .value_kind:     hidden_remainder_z
      - .offset:         208
        .size:           8
        .value_kind:     hidden_global_offset_x
      - .offset:         216
        .size:           8
        .value_kind:     hidden_global_offset_y
      - .offset:         224
        .size:           8
        .value_kind:     hidden_global_offset_z
      - .offset:         232
        .size:           2
        .value_kind:     hidden_grid_dims
      - .offset:         256
        .size:           8
        .value_kind:     hidden_multigrid_sync_arg
      - .offset:         288
        .size:           4
        .value_kind:     hidden_dynamic_lds_size
    .group_segment_fixed_size: 0
    .kernarg_segment_align: 8
    .kernarg_segment_size: 424
    .language:       OpenCL C
    .language_version:
      - 2
      - 0
    .max_flat_workgroup_size: 512
    .name:           _Z14fwd_megakernel6Params
    .private_segment_fixed_size: 0
    .sgpr_count:     104
    .sgpr_spill_count: 5
    .symbol:         _Z14fwd_megakernel6Params.kd
    .uniform_work_group_size: 1
    .uses_dynamic_stack: false
    .vgpr_count:     256
    .vgpr_spill_count: 0
    .wavefront_size: 64
